# scan recurrence loop rewritten by hand: LDS record loads as one burst a full step ahead, no hazard-free nops, y capture via DPP bank mask
# speedup vs baseline: 1.0339x; 1.0339x over previous
; __device__ __forceinline__ void scan_half(const Params& p, LAS unsigned char* lds, int pi, int rh, int pass) {
;     ...
;         const int j = lane & 7, rowl = 8 * wave + (lane >> 3);
;         float* stp = (float*)(WSP + WS_ST) + ((size_t)(pi * 64 + 32 * rh + rowl)) * 64 + 8 * j;
;         f32x2 P01 = (f32x2){0.f, 0.f}, P23 = P01, P45 = P01, P67 = P01;
;         if (pass == 1) { const f32x4 a = *(const f32x4*)stp, c = *(const f32x4*)(stp + 4); P01 = a.xy; P23 = a.zw; P45 = c.xy; P67 = c.zw; }
;         const bool first = (lane & 7) == 0;
;         SCAN_BAR;
;         for (int it = 0; it < 66; ++it) {
;             if (it < 64) {
;                 const LAS float* rec = REC + (it & 1) * REC_BUF + 8 * j; const LAS float* vvp = VV + (it & 3) * 1024 + rowl; LAS float* yyp = YY + (it & 3) * 1024 + rowl;
;                 const LAS float* ssp = SSP + (it & 1) * 64 + 2 * (lane & 31);
;                 const float inv2 = __builtin_amdgcn_rcpf(fmaxf(ssp[0] + ssp[1], 1e-24f));
;                 f32x4 Rkk[2][2], Rw[2][2], Rka[2][2], Rkm[2][2], Rr[2][2]; float Rv[2];
;     ...
;                 LOADREC(0, 0);
;                 float yp = 0.f, yk0 = 0.f, yk1 = 0.f, yk2 = 0.f, yk3 = 0.f;
;     ...
; #pragma unroll
;                 for (int s = 0; s < 32; ++s) {
;                     const int c = s & 1, pc = c ^ 1;
;                     const float si = __int_as_float(__builtin_amdgcn_readlane(__float_as_int(inv2), s));
;                     f32x2 px, py, t01, t23, t45, t67; float x;
;                     f32x2 vv2; vv2.x = Rv[c]; asm volatile("" : "+v"(vv2));
;                     if (s >= 1) {
;                         VPKMUL(px, P01, Rkk[c][0].xy); VPKMUL(py, P01, Rr[pc][0].xy); VPKFMA(px, P23, Rkk[c][0].zw, px); VPKFMA(py, P23, Rr[pc][0].zw, py);
;                         VPKFMA(px, P45, Rkk[c][1].xy, px); VPKFMA(py, P45, Rr[pc][1].xy, py); VPKFMA(px, P67, Rkk[c][1].zw, px); VPKFMA(py, P67, Rr[pc][1].zw, py);
;                         VADD(x, px.x, px.y); VADD(yp, py.x, py.y);
;                     } else {
;                         VPKMUL(px, P01, Rkk[c][0].xy); VPKFMA(px, P23, Rkk[c][0].zw, px); VPKFMA(px, P45, Rkk[c][1].xy, px); VPKFMA(px, P67, Rkk[c][1].zw, px);
;                         VADD(x, px.x, px.y);
;                     }
;                     asm volatile("" ::: "memory");
;                     if (s + 1 < 32) LOADREC((s + 1) & 1, s + 1);
.LBB0_1048:
	v_lshlrev_b32_e32 v8, 2, v8
	s_waitcnt lgkmcnt(0)
	s_barrier
	v_add_u32_e32 v29, s53, v8
	v_add_u32_e32 v30, s83, v8
	v_lshrrev_b32_e32 v10, 2, v9
	v_lshl_add_u32 v30, v10, 7, v30
	v_lshlrev_b32_e32 v10, 3, v113
	v_and_b32_e32 v10, 0xf8, v10
	v_mov_b32_e32 v28, v132
	v_add_u32_e32 v31, 0x21800, v10
	s_mov_b32 s9, 0
	s_waitcnt vmcnt(0)
.Lscan_it:
	s_cmp_gt_u32 s9, 63
	s_cbranch_scc1 .Lscan_bar
	s_and_b32 s10, s9, 1
	s_lshl_b32 s11, s10, 8
	v_add_u32_e32 v8, s11, v31
	ds_read_b64 v[8:9], v8
	s_mul_i32 s11, s10, 0xaa00
	s_and_b32 s10, s9, 3
	s_lshl_b32 s10, s10, 12
	v_add_u32_e32 v35, s11, v28
	v_add_u32_e32 v36, s10, v29
	v_add_u32_e32 v37, s10, v30
	ds_read_b128 v[48:51], v35 offset:0
	ds_read_b128 v[52:55], v35 offset:16
	ds_read_b128 v[72:75], v35 offset:26112
	ds_read_b128 v[76:79], v35 offset:26128
	ds_read_b32 v146, v36 offset:0
	ds_read_b128 v[56:59], v35 offset:8704
	ds_read_b128 v[60:63], v35 offset:8720
	ds_read_b128 v[64:67], v35 offset:17408
	ds_read_b128 v[68:71], v35 offset:17424
	ds_read_b128 v[114:117], v35 offset:34816
	ds_read_b128 v[118:121], v35 offset:34832
	s_waitcnt lgkmcnt(11)
	v_add_f32_e32 v8, v8, v9
	v_max_f32_e32 v8, 0x179abe15, v8
	v_rcp_f32_e32 v34, v8
	s_waitcnt lgkmcnt(0)
	ds_read_b128 v[80:83], v35 offset:272
	ds_read_b128 v[84:87], v35 offset:288
	ds_read_b128 v[104:107], v35 offset:26384
	ds_read_b128 v[108:111], v35 offset:26400
	ds_read_b32 v148, v36 offset:128
	ds_read_b128 v[88:91], v35 offset:8976
	ds_read_b128 v[92:95], v35 offset:8992
	ds_read_b128 v[96:99], v35 offset:17680
	ds_read_b128 v[100:103], v35 offset:17696
	ds_read_b128 v[122:125], v35 offset:35088
	ds_read_b128 v[126:129], v35 offset:35104
	v_pk_mul_f32 v[8:9], v[4:5], v[48:49]
	v_pk_fma_f32 v[8:9], v[6:7], v[50:51], v[8:9]
	v_pk_fma_f32 v[8:9], v[0:1], v[52:53], v[8:9]
	v_pk_fma_f32 v[8:9], v[2:3], v[54:55], v[8:9]
	v_add_f32_e32 v12, v8, v9
	v_readlane_b32 s8, v34, 0
	v_pk_mul_f32 v[16:17], v[146:147], v[72:73] op_sel_hi:[0,1]
	v_pk_mul_f32 v[18:19], v[146:147], v[74:75] op_sel_hi:[0,1]
	v_add_f32_dpp v12, v12, v12 quad_perm:[1,0,3,2] row_mask:0xf bank_mask:0xf bound_ctrl:1
	v_pk_mul_f32 v[20:21], v[146:147], v[76:77] op_sel_hi:[0,1]
	v_pk_mul_f32 v[22:23], v[146:147], v[78:79] op_sel_hi:[0,1]
	v_add_f32_dpp v12, v12, v12 quad_perm:[2,3,0,1] row_mask:0xf bank_mask:0xf bound_ctrl:1
	v_pk_fma_f32 v[4:5], v[4:5], v[56:57], v[16:17]
	v_pk_fma_f32 v[6:7], v[6:7], v[58:59], v[18:19]
	v_add_f32_dpp v12, v12, v12 row_half_mirror row_mask:0xf bank_mask:0xf bound_ctrl:1
	v_pk_fma_f32 v[0:1], v[0:1], v[60:61], v[20:21]
	v_pk_fma_f32 v[2:3], v[2:3], v[62:63], v[22:23]
	v_mul_f32_e32 v12, s8, v12
	v_pk_fma_f32 v[4:5], v[12:13], v[64:65], v[4:5] op_sel_hi:[0,1,1] neg_lo:[1,0,0] neg_hi:[1,0,0]
	v_pk_fma_f32 v[6:7], v[12:13], v[66:67], v[6:7] op_sel_hi:[0,1,1] neg_lo:[1,0,0] neg_hi:[1,0,0]
	v_pk_fma_f32 v[0:1], v[12:13], v[68:69], v[0:1] op_sel_hi:[0,1,1] neg_lo:[1,0,0] neg_hi:[1,0,0]
	v_pk_fma_f32 v[2:3], v[12:13], v[70:71], v[2:3] op_sel_hi:[0,1,1] neg_lo:[1,0,0] neg_hi:[1,0,0]
	s_waitcnt lgkmcnt(0)
	ds_read_b128 v[48:51], v35 offset:544
	ds_read_b128 v[52:55], v35 offset:560
	ds_read_b128 v[72:75], v35 offset:26656
	ds_read_b128 v[76:79], v35 offset:26672
	ds_read_b32 v146, v36 offset:256
	ds_read_b128 v[56:59], v35 offset:9248
	ds_read_b128 v[60:63], v35 offset:9264
	ds_read_b128 v[64:67], v35 offset:17952
	ds_read_b128 v[68:71], v35 offset:17968
	ds_read_b128 v[138:141], v35 offset:35360
	ds_read_b128 v[142:145], v35 offset:35376
	v_pk_mul_f32 v[8:9], v[4:5], v[80:81]
	v_pk_mul_f32 v[10:11], v[4:5], v[114:115]
	v_pk_fma_f32 v[8:9], v[6:7], v[82:83], v[8:9]
	v_pk_fma_f32 v[10:11], v[6:7], v[116:117], v[10:11]
	v_pk_fma_f32 v[8:9], v[0:1], v[84:85], v[8:9]
	v_pk_fma_f32 v[10:11], v[0:1], v[118:119], v[10:11]
	v_pk_fma_f32 v[8:9], v[2:3], v[86:87], v[8:9]
	v_pk_fma_f32 v[10:11], v[2:3], v[120:121], v[10:11]
	v_add_f32_e32 v12, v8, v9
	v_add_f32_e32 v14, v10, v11
	v_readlane_b32 s8, v34, 1
	v_pk_mul_f32 v[16:17], v[148:149], v[104:105] op_sel_hi:[0,1]
	v_pk_mul_f32 v[18:19], v[148:149], v[106:107] op_sel_hi:[0,1]
	v_add_f32_dpp v12, v12, v12 quad_perm:[1,0,3,2] row_mask:0xf bank_mask:0xf bound_ctrl:1
	v_add_f32_dpp v14, v14, v14 quad_perm:[1,0,3,2] row_mask:0xf bank_mask:0xf bound_ctrl:1
	v_pk_mul_f32 v[20:21], v[148:149], v[108:109] op_sel_hi:[0,1]
	v_pk_mul_f32 v[22:23], v[148:149], v[110:111] op_sel_hi:[0,1]
	v_add_f32_dpp v12, v12, v12 quad_perm:[2,3,0,1] row_mask:0xf bank_mask:0xf bound_ctrl:1
	v_add_f32_dpp v14, v14, v14 quad_perm:[2,3,0,1] row_mask:0xf bank_mask:0xf bound_ctrl:1
	v_pk_fma_f32 v[4:5], v[4:5], v[88:89], v[16:17]
	v_pk_fma_f32 v[6:7], v[6:7], v[90:91], v[18:19]
	v_add_f32_dpp v12, v12, v12 row_half_mirror row_mask:0xf bank_mask:0xf bound_ctrl:1
	v_add_f32_dpp v40, v14, v14 row_half_mirror row_mask:0xf bank_mask:0x5 bound_ctrl:1
	v_pk_fma_f32 v[0:1], v[0:1], v[92:93], v[20:21]
	v_pk_fma_f32 v[2:3], v[2:3], v[94:95], v[22:23]
	v_mul_f32_e32 v12, s8, v12
	v_pk_fma_f32 v[4:5], v[12:13], v[96:97], v[4:5] op_sel_hi:[0,1,1] neg_lo:[1,0,0] neg_hi:[1,0,0]
	v_pk_fma_f32 v[6:7], v[12:13], v[98:99], v[6:7] op_sel_hi:[0,1,1] neg_lo:[1,0,0] neg_hi:[1,0,0]
	v_pk_fma_f32 v[0:1], v[12:13], v[100:101], v[0:1] op_sel_hi:[0,1,1] neg_lo:[1,0,0] neg_hi:[1,0,0]
	v_pk_fma_f32 v[2:3], v[12:13], v[102:103], v[2:3] op_sel_hi:[0,1,1] neg_lo:[1,0,0] neg_hi:[1,0,0]
	s_waitcnt lgkmcnt(0)
; __device__ __forceinline__ void scan_half(const Params& p, LAS unsigned char* lds, int pi, int rh, int pass) {
;     ...
;                 for (int s = 0; s < 32; ++s) {
;                     const int c = s & 1, pc = c ^ 1;
;                     const float si = __int_as_float(__builtin_amdgcn_readlane(__float_as_int(inv2), s));
;                     f32x2 px, py, t01, t23, t45, t67; float x;
;                     f32x2 vv2; vv2.x = Rv[c]; asm volatile("" : "+v"(vv2));
;                     if (s >= 1) {
;                         VPKMUL(px, P01, Rkk[c][0].xy); VPKMUL(py, P01, Rr[pc][0].xy); VPKFMA(px, P23, Rkk[c][0].zw, px); VPKFMA(py, P23, Rr[pc][0].zw, py);
;                         VPKFMA(px, P45, Rkk[c][1].xy, px); VPKFMA(py, P45, Rr[pc][1].xy, py); VPKFMA(px, P67, Rkk[c][1].zw, px); VPKFMA(py, P67, Rr[pc][1].zw, py);
;                         VADD(x, px.x, px.y); VADD(yp, py.x, py.y);
;                     } else {
;                         VPKMUL(px, P01, Rkk[c][0].xy); VPKFMA(px, P23, Rkk[c][0].zw, px); VPKFMA(px, P45, Rkk[c][1].xy, px); VPKFMA(px, P67, Rkk[c][1].zw, px);
;                         VADD(x, px.x, px.y);
;                     }
;                     asm volatile("" ::: "memory");
;                     if (s + 1 < 32) LOADREC((s + 1) & 1, s + 1);
;                     asm volatile("" ::: "memory");
;                     VPKMULBL(t01, vv2, Rkm[c][0].xy); VPKMULBL(t23, vv2, Rkm[c][0].zw);
;                     VDPP1(x); if (s >= 1) VDPP1(yp);
;                     VPKMULBL(t45, vv2, Rkm[c][1].xy); VPKMULBL(t67, vv2, Rkm[c][1].zw);
;                     VDPP2(x); if (s >= 1) VDPP2(yp);
;                     VPKFMA(P01, P01, Rw[c][0].xy, t01); VPKFMA(P23, P23, Rw[c][0].zw, t23);
;                     VDPP3(x); if (s >= 1) VDPP3(yp);
;                     VPKFMA(P45, P45, Rw[c][1].xy, t45); VPKFMA(P67, P67, Rw[c][1].zw, t67);
;                     if (s >= 1) { if (s - 1 < 8) YSHIFT(yk0); else if (s - 1 < 16) YSHIFT(yk1); else if (s - 1 < 24) YSHIFT(yk2); else YSHIFT(yk3); }
;                     x = x * si;
;                     f32x2 x2; x2.x = x; asm volatile("" : "+v"(x2));
;                     VPKNFMABL(P01, x2, Rka[c][0].xy, P01); VPKNFMABL(P23, x2, Rka[c][0].zw, P23); VPKNFMABL(P45, x2, Rka[c][1].xy, P45); VPKNFMABL(P67, x2, Rka[c][1].zw, P67);
;                 }
	ds_read_b128 v[80:83], v35 offset:816
	ds_read_b128 v[84:87], v35 offset:832
	ds_read_b128 v[104:107], v35 offset:26928
	ds_read_b128 v[108:111], v35 offset:26944
	ds_read_b32 v148, v36 offset:384
	ds_read_b128 v[88:91], v35 offset:9520
	ds_read_b128 v[92:95], v35 offset:9536
	ds_read_b128 v[96:99], v35 offset:18224
	ds_read_b128 v[100:103], v35 offset:18240
	ds_read_b128 v[114:117], v35 offset:35632
	ds_read_b128 v[118:121], v35 offset:35648
	v_pk_mul_f32 v[8:9], v[4:5], v[48:49]
	v_pk_mul_f32 v[10:11], v[4:5], v[122:123]
	v_pk_fma_f32 v[8:9], v[6:7], v[50:51], v[8:9]
	v_pk_fma_f32 v[10:11], v[6:7], v[124:125], v[10:11]
	v_pk_fma_f32 v[8:9], v[0:1], v[52:53], v[8:9]
	v_pk_fma_f32 v[10:11], v[0:1], v[126:127], v[10:11]
	v_pk_fma_f32 v[8:9], v[2:3], v[54:55], v[8:9]
	v_pk_fma_f32 v[10:11], v[2:3], v[128:129], v[10:11]
	v_add_f32_e32 v12, v8, v9
	v_add_f32_e32 v14, v10, v11
	v_readlane_b32 s8, v34, 2
	v_pk_mul_f32 v[16:17], v[146:147], v[72:73] op_sel_hi:[0,1]
	v_pk_mul_f32 v[18:19], v[146:147], v[74:75] op_sel_hi:[0,1]
	v_add_f32_dpp v12, v12, v12 quad_perm:[1,0,3,2] row_mask:0xf bank_mask:0xf bound_ctrl:1
	v_add_f32_dpp v14, v14, v14 quad_perm:[1,0,3,2] row_mask:0xf bank_mask:0xf bound_ctrl:1
	v_pk_mul_f32 v[20:21], v[146:147], v[76:77] op_sel_hi:[0,1]
	v_pk_mul_f32 v[22:23], v[146:147], v[78:79] op_sel_hi:[0,1]
	v_add_f32_dpp v12, v12, v12 quad_perm:[2,3,0,1] row_mask:0xf bank_mask:0xf bound_ctrl:1
	v_add_f32_dpp v14, v14, v14 quad_perm:[2,3,0,1] row_mask:0xf bank_mask:0xf bound_ctrl:1
	v_pk_fma_f32 v[4:5], v[4:5], v[56:57], v[16:17]
	v_pk_fma_f32 v[6:7], v[6:7], v[58:59], v[18:19]
	v_add_f32_dpp v12, v12, v12 row_half_mirror row_mask:0xf bank_mask:0xf bound_ctrl:1
	v_add_f32_dpp v40, v14, v14 row_half_mirror row_mask:0xf bank_mask:0xa bound_ctrl:1
	v_pk_fma_f32 v[0:1], v[0:1], v[60:61], v[20:21]
	v_pk_fma_f32 v[2:3], v[2:3], v[62:63], v[22:23]
	v_mul_f32_e32 v12, s8, v12
	v_pk_fma_f32 v[4:5], v[12:13], v[64:65], v[4:5] op_sel_hi:[0,1,1] neg_lo:[1,0,0] neg_hi:[1,0,0]
	v_pk_fma_f32 v[6:7], v[12:13], v[66:67], v[6:7] op_sel_hi:[0,1,1] neg_lo:[1,0,0] neg_hi:[1,0,0]
	v_pk_fma_f32 v[0:1], v[12:13], v[68:69], v[0:1] op_sel_hi:[0,1,1] neg_lo:[1,0,0] neg_hi:[1,0,0]
	v_pk_fma_f32 v[2:3], v[12:13], v[70:71], v[2:3] op_sel_hi:[0,1,1] neg_lo:[1,0,0] neg_hi:[1,0,0]
	s_waitcnt lgkmcnt(0)
	ds_read_b128 v[48:51], v35 offset:1088
	ds_read_b128 v[52:55], v35 offset:1104
	ds_read_b128 v[72:75], v35 offset:27200
	ds_read_b128 v[76:79], v35 offset:27216
	ds_read_b32 v146, v36 offset:512
	ds_read_b128 v[56:59], v35 offset:9792
	ds_read_b128 v[60:63], v35 offset:9808
	ds_read_b128 v[64:67], v35 offset:18496
	ds_read_b128 v[68:71], v35 offset:18512
	ds_read_b128 v[122:125], v35 offset:35904
	ds_read_b128 v[126:129], v35 offset:35920
	v_pk_mul_f32 v[8:9], v[4:5], v[80:81]
	v_pk_mul_f32 v[10:11], v[4:5], v[138:139]
	v_pk_fma_f32 v[8:9], v[6:7], v[82:83], v[8:9]
	v_pk_fma_f32 v[10:11], v[6:7], v[140:141], v[10:11]
	v_pk_fma_f32 v[8:9], v[0:1], v[84:85], v[8:9]
	v_pk_fma_f32 v[10:11], v[0:1], v[142:143], v[10:11]
	v_pk_fma_f32 v[8:9], v[2:3], v[86:87], v[8:9]
	v_pk_fma_f32 v[10:11], v[2:3], v[144:145], v[10:11]
	v_add_f32_e32 v12, v8, v9
	v_add_f32_e32 v14, v10, v11
	v_readlane_b32 s8, v34, 3
	v_pk_mul_f32 v[16:17], v[148:149], v[104:105] op_sel_hi:[0,1]
	v_pk_mul_f32 v[18:19], v[148:149], v[106:107] op_sel_hi:[0,1]
	v_add_f32_dpp v12, v12, v12 quad_perm:[1,0,3,2] row_mask:0xf bank_mask:0xf bound_ctrl:1
	v_add_f32_dpp v14, v14, v14 quad_perm:[1,0,3,2] row_mask:0xf bank_mask:0xf bound_ctrl:1
	v_pk_mul_f32 v[20:21], v[148:149], v[108:109] op_sel_hi:[0,1]
	v_pk_mul_f32 v[22:23], v[148:149], v[110:111] op_sel_hi:[0,1]
	v_add_f32_dpp v12, v12, v12 quad_perm:[2,3,0,1] row_mask:0xf bank_mask:0xf bound_ctrl:1
	v_add_f32_dpp v14, v14, v14 quad_perm:[2,3,0,1] row_mask:0xf bank_mask:0xf bound_ctrl:1
	v_pk_fma_f32 v[4:5], v[4:5], v[88:89], v[16:17]
	v_pk_fma_f32 v[6:7], v[6:7], v[90:91], v[18:19]
	v_add_f32_dpp v12, v12, v12 row_half_mirror row_mask:0xf bank_mask:0xf bound_ctrl:1
	v_add_f32_dpp v41, v14, v14 row_half_mirror row_mask:0xf bank_mask:0x5 bound_ctrl:1
	v_pk_fma_f32 v[0:1], v[0:1], v[92:93], v[20:21]
	v_pk_fma_f32 v[2:3], v[2:3], v[94:95], v[22:23]
	v_mul_f32_e32 v12, s8, v12
	v_pk_fma_f32 v[4:5], v[12:13], v[96:97], v[4:5] op_sel_hi:[0,1,1] neg_lo:[1,0,0] neg_hi:[1,0,0]
	v_pk_fma_f32 v[6:7], v[12:13], v[98:99], v[6:7] op_sel_hi:[0,1,1] neg_lo:[1,0,0] neg_hi:[1,0,0]
	v_pk_fma_f32 v[0:1], v[12:13], v[100:101], v[0:1] op_sel_hi:[0,1,1] neg_lo:[1,0,0] neg_hi:[1,0,0]
	v_pk_fma_f32 v[2:3], v[12:13], v[102:103], v[2:3] op_sel_hi:[0,1,1] neg_lo:[1,0,0] neg_hi:[1,0,0]
	s_waitcnt lgkmcnt(0)
; __device__ __forceinline__ void scan_half(const Params& p, LAS unsigned char* lds, int pi, int rh, int pass) {
;     ...
;                 for (int s = 0; s < 32; ++s) {
;                     const int c = s & 1, pc = c ^ 1;
;                     const float si = __int_as_float(__builtin_amdgcn_readlane(__float_as_int(inv2), s));
;                     f32x2 px, py, t01, t23, t45, t67; float x;
;                     f32x2 vv2; vv2.x = Rv[c]; asm volatile("" : "+v"(vv2));
;                     if (s >= 1) {
;                         VPKMUL(px, P01, Rkk[c][0].xy); VPKMUL(py, P01, Rr[pc][0].xy); VPKFMA(px, P23, Rkk[c][0].zw, px); VPKFMA(py, P23, Rr[pc][0].zw, py);
;                         VPKFMA(px, P45, Rkk[c][1].xy, px); VPKFMA(py, P45, Rr[pc][1].xy, py); VPKFMA(px, P67, Rkk[c][1].zw, px); VPKFMA(py, P67, Rr[pc][1].zw, py);
;                         VADD(x, px.x, px.y); VADD(yp, py.x, py.y);
;                     } else {
;                         VPKMUL(px, P01, Rkk[c][0].xy); VPKFMA(px, P23, Rkk[c][0].zw, px); VPKFMA(px, P45, Rkk[c][1].xy, px); VPKFMA(px, P67, Rkk[c][1].zw, px);
;                         VADD(x, px.x, px.y);
;                     }
;                     asm volatile("" ::: "memory");
;                     if (s + 1 < 32) LOADREC((s + 1) & 1, s + 1);
;                     asm volatile("" ::: "memory");
;                     VPKMULBL(t01, vv2, Rkm[c][0].xy); VPKMULBL(t23, vv2, Rkm[c][0].zw);
;                     VDPP1(x); if (s >= 1) VDPP1(yp);
;                     VPKMULBL(t45, vv2, Rkm[c][1].xy); VPKMULBL(t67, vv2, Rkm[c][1].zw);
;                     VDPP2(x); if (s >= 1) VDPP2(yp);
;                     VPKFMA(P01, P01, Rw[c][0].xy, t01); VPKFMA(P23, P23, Rw[c][0].zw, t23);
;                     VDPP3(x); if (s >= 1) VDPP3(yp);
;                     VPKFMA(P45, P45, Rw[c][1].xy, t45); VPKFMA(P67, P67, Rw[c][1].zw, t67);
;                     if (s >= 1) { if (s - 1 < 8) YSHIFT(yk0); else if (s - 1 < 16) YSHIFT(yk1); else if (s - 1 < 24) YSHIFT(yk2); else YSHIFT(yk3); }
;                     x = x * si;
;                     f32x2 x2; x2.x = x; asm volatile("" : "+v"(x2));
;                     VPKNFMABL(P01, x2, Rka[c][0].xy, P01); VPKNFMABL(P23, x2, Rka[c][0].zw, P23); VPKNFMABL(P45, x2, Rka[c][1].xy, P45); VPKNFMABL(P67, x2, Rka[c][1].zw, P67);
;                 }
	ds_read_b128 v[80:83], v35 offset:1360
	ds_read_b128 v[84:87], v35 offset:1376
	ds_read_b128 v[104:107], v35 offset:27472
	ds_read_b128 v[108:111], v35 offset:27488
	ds_read_b32 v148, v36 offset:640
	ds_read_b128 v[88:91], v35 offset:10064
	ds_read_b128 v[92:95], v35 offset:10080
	ds_read_b128 v[96:99], v35 offset:18768
	ds_read_b128 v[100:103], v35 offset:18784
	ds_read_b128 v[138:141], v35 offset:36176
	ds_read_b128 v[142:145], v35 offset:36192
	v_pk_mul_f32 v[8:9], v[4:5], v[48:49]
	v_pk_mul_f32 v[10:11], v[4:5], v[114:115]
	v_pk_fma_f32 v[8:9], v[6:7], v[50:51], v[8:9]
	v_pk_fma_f32 v[10:11], v[6:7], v[116:117], v[10:11]
	v_pk_fma_f32 v[8:9], v[0:1], v[52:53], v[8:9]
	v_pk_fma_f32 v[10:11], v[0:1], v[118:119], v[10:11]
	v_pk_fma_f32 v[8:9], v[2:3], v[54:55], v[8:9]
	v_pk_fma_f32 v[10:11], v[2:3], v[120:121], v[10:11]
	v_add_f32_e32 v12, v8, v9
	v_add_f32_e32 v14, v10, v11
	v_readlane_b32 s8, v34, 4
	v_pk_mul_f32 v[16:17], v[146:147], v[72:73] op_sel_hi:[0,1]
	v_pk_mul_f32 v[18:19], v[146:147], v[74:75] op_sel_hi:[0,1]
	v_add_f32_dpp v12, v12, v12 quad_perm:[1,0,3,2] row_mask:0xf bank_mask:0xf bound_ctrl:1
	v_add_f32_dpp v14, v14, v14 quad_perm:[1,0,3,2] row_mask:0xf bank_mask:0xf bound_ctrl:1
	v_pk_mul_f32 v[20:21], v[146:147], v[76:77] op_sel_hi:[0,1]
	v_pk_mul_f32 v[22:23], v[146:147], v[78:79] op_sel_hi:[0,1]
	v_add_f32_dpp v12, v12, v12 quad_perm:[2,3,0,1] row_mask:0xf bank_mask:0xf bound_ctrl:1
	v_add_f32_dpp v14, v14, v14 quad_perm:[2,3,0,1] row_mask:0xf bank_mask:0xf bound_ctrl:1
	v_pk_fma_f32 v[4:5], v[4:5], v[56:57], v[16:17]
	v_pk_fma_f32 v[6:7], v[6:7], v[58:59], v[18:19]
	v_add_f32_dpp v12, v12, v12 row_half_mirror row_mask:0xf bank_mask:0xf bound_ctrl:1
	v_add_f32_dpp v41, v14, v14 row_half_mirror row_mask:0xf bank_mask:0xa bound_ctrl:1
	v_pk_fma_f32 v[0:1], v[0:1], v[60:61], v[20:21]
	v_pk_fma_f32 v[2:3], v[2:3], v[62:63], v[22:23]
	v_mul_f32_e32 v12, s8, v12
	v_pk_fma_f32 v[4:5], v[12:13], v[64:65], v[4:5] op_sel_hi:[0,1,1] neg_lo:[1,0,0] neg_hi:[1,0,0]
	v_pk_fma_f32 v[6:7], v[12:13], v[66:67], v[6:7] op_sel_hi:[0,1,1] neg_lo:[1,0,0] neg_hi:[1,0,0]
	v_pk_fma_f32 v[0:1], v[12:13], v[68:69], v[0:1] op_sel_hi:[0,1,1] neg_lo:[1,0,0] neg_hi:[1,0,0]
	v_pk_fma_f32 v[2:3], v[12:13], v[70:71], v[2:3] op_sel_hi:[0,1,1] neg_lo:[1,0,0] neg_hi:[1,0,0]
	s_waitcnt lgkmcnt(0)
	ds_read_b128 v[48:51], v35 offset:1632
	ds_read_b128 v[52:55], v35 offset:1648
	ds_read_b128 v[72:75], v35 offset:27744
	ds_read_b128 v[76:79], v35 offset:27760
	ds_read_b32 v146, v36 offset:768
	ds_read_b128 v[56:59], v35 offset:10336
	ds_read_b128 v[60:63], v35 offset:10352
	ds_read_b128 v[64:67], v35 offset:19040
	ds_read_b128 v[68:71], v35 offset:19056
	ds_read_b128 v[114:117], v35 offset:36448
	ds_read_b128 v[118:121], v35 offset:36464
	v_pk_mul_f32 v[8:9], v[4:5], v[80:81]
	v_pk_mul_f32 v[10:11], v[4:5], v[122:123]
	v_pk_fma_f32 v[8:9], v[6:7], v[82:83], v[8:9]
	v_pk_fma_f32 v[10:11], v[6:7], v[124:125], v[10:11]
	v_pk_fma_f32 v[8:9], v[0:1], v[84:85], v[8:9]
	v_pk_fma_f32 v[10:11], v[0:1], v[126:127], v[10:11]
	v_pk_fma_f32 v[8:9], v[2:3], v[86:87], v[8:9]
	v_pk_fma_f32 v[10:11], v[2:3], v[128:129], v[10:11]
	v_add_f32_e32 v12, v8, v9
	v_add_f32_e32 v14, v10, v11
	v_readlane_b32 s8, v34, 5
	v_pk_mul_f32 v[16:17], v[148:149], v[104:105] op_sel_hi:[0,1]
	v_pk_mul_f32 v[18:19], v[148:149], v[106:107] op_sel_hi:[0,1]
	v_add_f32_dpp v12, v12, v12 quad_perm:[1,0,3,2] row_mask:0xf bank_mask:0xf bound_ctrl:1
	v_add_f32_dpp v14, v14, v14 quad_perm:[1,0,3,2] row_mask:0xf bank_mask:0xf bound_ctrl:1
	v_pk_mul_f32 v[20:21], v[148:149], v[108:109] op_sel_hi:[0,1]
	v_pk_mul_f32 v[22:23], v[148:149], v[110:111] op_sel_hi:[0,1]
	v_add_f32_dpp v12, v12, v12 quad_perm:[2,3,0,1] row_mask:0xf bank_mask:0xf bound_ctrl:1
	v_add_f32_dpp v14, v14, v14 quad_perm:[2,3,0,1] row_mask:0xf bank_mask:0xf bound_ctrl:1
	v_pk_fma_f32 v[4:5], v[4:5], v[88:89], v[16:17]
	v_pk_fma_f32 v[6:7], v[6:7], v[90:91], v[18:19]
	v_add_f32_dpp v12, v12, v12 row_half_mirror row_mask:0xf bank_mask:0xf bound_ctrl:1
	v_add_f32_dpp v42, v14, v14 row_half_mirror row_mask:0xf bank_mask:0x5 bound_ctrl:1
	v_pk_fma_f32 v[0:1], v[0:1], v[92:93], v[20:21]
	v_pk_fma_f32 v[2:3], v[2:3], v[94:95], v[22:23]
	v_mul_f32_e32 v12, s8, v12
	v_pk_fma_f32 v[4:5], v[12:13], v[96:97], v[4:5] op_sel_hi:[0,1,1] neg_lo:[1,0,0] neg_hi:[1,0,0]
	v_pk_fma_f32 v[6:7], v[12:13], v[98:99], v[6:7] op_sel_hi:[0,1,1] neg_lo:[1,0,0] neg_hi:[1,0,0]
	v_pk_fma_f32 v[0:1], v[12:13], v[100:101], v[0:1] op_sel_hi:[0,1,1] neg_lo:[1,0,0] neg_hi:[1,0,0]
	v_pk_fma_f32 v[2:3], v[12:13], v[102:103], v[2:3] op_sel_hi:[0,1,1] neg_lo:[1,0,0] neg_hi:[1,0,0]
	s_waitcnt lgkmcnt(0)
; __device__ __forceinline__ void scan_half(const Params& p, LAS unsigned char* lds, int pi, int rh, int pass) {
;     ...
;                 for (int s = 0; s < 32; ++s) {
;                     const int c = s & 1, pc = c ^ 1;
;                     const float si = __int_as_float(__builtin_amdgcn_readlane(__float_as_int(inv2), s));
;                     f32x2 px, py, t01, t23, t45, t67; float x;
;                     f32x2 vv2; vv2.x = Rv[c]; asm volatile("" : "+v"(vv2));
;                     if (s >= 1) {
;                         VPKMUL(px, P01, Rkk[c][0].xy); VPKMUL(py, P01, Rr[pc][0].xy); VPKFMA(px, P23, Rkk[c][0].zw, px); VPKFMA(py, P23, Rr[pc][0].zw, py);
;                         VPKFMA(px, P45, Rkk[c][1].xy, px); VPKFMA(py, P45, Rr[pc][1].xy, py); VPKFMA(px, P67, Rkk[c][1].zw, px); VPKFMA(py, P67, Rr[pc][1].zw, py);
;                         VADD(x, px.x, px.y); VADD(yp, py.x, py.y);
;                     } else {
;                         VPKMUL(px, P01, Rkk[c][0].xy); VPKFMA(px, P23, Rkk[c][0].zw, px); VPKFMA(px, P45, Rkk[c][1].xy, px); VPKFMA(px, P67, Rkk[c][1].zw, px);
;                         VADD(x, px.x, px.y);
;                     }
;                     asm volatile("" ::: "memory");
;                     if (s + 1 < 32) LOADREC((s + 1) & 1, s + 1);
;                     asm volatile("" ::: "memory");
;                     VPKMULBL(t01, vv2, Rkm[c][0].xy); VPKMULBL(t23, vv2, Rkm[c][0].zw);
;                     VDPP1(x); if (s >= 1) VDPP1(yp);
;                     VPKMULBL(t45, vv2, Rkm[c][1].xy); VPKMULBL(t67, vv2, Rkm[c][1].zw);
;                     VDPP2(x); if (s >= 1) VDPP2(yp);
;                     VPKFMA(P01, P01, Rw[c][0].xy, t01); VPKFMA(P23, P23, Rw[c][0].zw, t23);
;                     VDPP3(x); if (s >= 1) VDPP3(yp);
;                     VPKFMA(P45, P45, Rw[c][1].xy, t45); VPKFMA(P67, P67, Rw[c][1].zw, t67);
;                     if (s >= 1) { if (s - 1 < 8) YSHIFT(yk0); else if (s - 1 < 16) YSHIFT(yk1); else if (s - 1 < 24) YSHIFT(yk2); else YSHIFT(yk3); }
;                     x = x * si;
;                     f32x2 x2; x2.x = x; asm volatile("" : "+v"(x2));
;                     VPKNFMABL(P01, x2, Rka[c][0].xy, P01); VPKNFMABL(P23, x2, Rka[c][0].zw, P23); VPKNFMABL(P45, x2, Rka[c][1].xy, P45); VPKNFMABL(P67, x2, Rka[c][1].zw, P67);
;                 }
	ds_read_b128 v[80:83], v35 offset:1904
	ds_read_b128 v[84:87], v35 offset:1920
	ds_read_b128 v[104:107], v35 offset:28016
	ds_read_b128 v[108:111], v35 offset:28032
	ds_read_b32 v148, v36 offset:896
	ds_read_b128 v[88:91], v35 offset:10608
	ds_read_b128 v[92:95], v35 offset:10624
	ds_read_b128 v[96:99], v35 offset:19312
	ds_read_b128 v[100:103], v35 offset:19328
	ds_read_b128 v[122:125], v35 offset:36720
	ds_read_b128 v[126:129], v35 offset:36736
	v_pk_mul_f32 v[8:9], v[4:5], v[48:49]
	v_pk_mul_f32 v[10:11], v[4:5], v[138:139]
	v_pk_fma_f32 v[8:9], v[6:7], v[50:51], v[8:9]
	v_pk_fma_f32 v[10:11], v[6:7], v[140:141], v[10:11]
	v_pk_fma_f32 v[8:9], v[0:1], v[52:53], v[8:9]
	v_pk_fma_f32 v[10:11], v[0:1], v[142:143], v[10:11]
	v_pk_fma_f32 v[8:9], v[2:3], v[54:55], v[8:9]
	v_pk_fma_f32 v[10:11], v[2:3], v[144:145], v[10:11]
	v_add_f32_e32 v12, v8, v9
	v_add_f32_e32 v14, v10, v11
	v_readlane_b32 s8, v34, 6
	v_pk_mul_f32 v[16:17], v[146:147], v[72:73] op_sel_hi:[0,1]
	v_pk_mul_f32 v[18:19], v[146:147], v[74:75] op_sel_hi:[0,1]
	v_add_f32_dpp v12, v12, v12 quad_perm:[1,0,3,2] row_mask:0xf bank_mask:0xf bound_ctrl:1
	v_add_f32_dpp v14, v14, v14 quad_perm:[1,0,3,2] row_mask:0xf bank_mask:0xf bound_ctrl:1
	v_pk_mul_f32 v[20:21], v[146:147], v[76:77] op_sel_hi:[0,1]
	v_pk_mul_f32 v[22:23], v[146:147], v[78:79] op_sel_hi:[0,1]
	v_add_f32_dpp v12, v12, v12 quad_perm:[2,3,0,1] row_mask:0xf bank_mask:0xf bound_ctrl:1
	v_add_f32_dpp v14, v14, v14 quad_perm:[2,3,0,1] row_mask:0xf bank_mask:0xf bound_ctrl:1
	v_pk_fma_f32 v[4:5], v[4:5], v[56:57], v[16:17]
	v_pk_fma_f32 v[6:7], v[6:7], v[58:59], v[18:19]
	v_add_f32_dpp v12, v12, v12 row_half_mirror row_mask:0xf bank_mask:0xf bound_ctrl:1
	v_add_f32_dpp v42, v14, v14 row_half_mirror row_mask:0xf bank_mask:0xa bound_ctrl:1
	v_pk_fma_f32 v[0:1], v[0:1], v[60:61], v[20:21]
	v_pk_fma_f32 v[2:3], v[2:3], v[62:63], v[22:23]
	v_mul_f32_e32 v12, s8, v12
	v_pk_fma_f32 v[4:5], v[12:13], v[64:65], v[4:5] op_sel_hi:[0,1,1] neg_lo:[1,0,0] neg_hi:[1,0,0]
	v_pk_fma_f32 v[6:7], v[12:13], v[66:67], v[6:7] op_sel_hi:[0,1,1] neg_lo:[1,0,0] neg_hi:[1,0,0]
	v_pk_fma_f32 v[0:1], v[12:13], v[68:69], v[0:1] op_sel_hi:[0,1,1] neg_lo:[1,0,0] neg_hi:[1,0,0]
	v_pk_fma_f32 v[2:3], v[12:13], v[70:71], v[2:3] op_sel_hi:[0,1,1] neg_lo:[1,0,0] neg_hi:[1,0,0]
	s_waitcnt lgkmcnt(0)
	ds_read_b128 v[48:51], v35 offset:2176
	ds_read_b128 v[52:55], v35 offset:2192
	ds_read_b128 v[72:75], v35 offset:28288
	ds_read_b128 v[76:79], v35 offset:28304
	ds_read_b32 v146, v36 offset:1024
	ds_read_b128 v[56:59], v35 offset:10880
	ds_read_b128 v[60:63], v35 offset:10896
	ds_read_b128 v[64:67], v35 offset:19584
	ds_read_b128 v[68:71], v35 offset:19600
	ds_read_b128 v[138:141], v35 offset:36992
	ds_read_b128 v[142:145], v35 offset:37008
	v_pk_mul_f32 v[8:9], v[4:5], v[80:81]
	v_pk_mul_f32 v[10:11], v[4:5], v[114:115]
	v_pk_fma_f32 v[8:9], v[6:7], v[82:83], v[8:9]
	v_pk_fma_f32 v[10:11], v[6:7], v[116:117], v[10:11]
	v_pk_fma_f32 v[8:9], v[0:1], v[84:85], v[8:9]
	v_pk_fma_f32 v[10:11], v[0:1], v[118:119], v[10:11]
	v_pk_fma_f32 v[8:9], v[2:3], v[86:87], v[8:9]
	v_pk_fma_f32 v[10:11], v[2:3], v[120:121], v[10:11]
	v_add_f32_e32 v12, v8, v9
	v_add_f32_e32 v14, v10, v11
	v_readlane_b32 s8, v34, 7
	v_pk_mul_f32 v[16:17], v[148:149], v[104:105] op_sel_hi:[0,1]
	v_pk_mul_f32 v[18:19], v[148:149], v[106:107] op_sel_hi:[0,1]
	v_add_f32_dpp v12, v12, v12 quad_perm:[1,0,3,2] row_mask:0xf bank_mask:0xf bound_ctrl:1
	v_add_f32_dpp v14, v14, v14 quad_perm:[1,0,3,2] row_mask:0xf bank_mask:0xf bound_ctrl:1
	v_pk_mul_f32 v[20:21], v[148:149], v[108:109] op_sel_hi:[0,1]
	v_pk_mul_f32 v[22:23], v[148:149], v[110:111] op_sel_hi:[0,1]
	v_add_f32_dpp v12, v12, v12 quad_perm:[2,3,0,1] row_mask:0xf bank_mask:0xf bound_ctrl:1
	v_add_f32_dpp v14, v14, v14 quad_perm:[2,3,0,1] row_mask:0xf bank_mask:0xf bound_ctrl:1
	v_pk_fma_f32 v[4:5], v[4:5], v[88:89], v[16:17]
	v_pk_fma_f32 v[6:7], v[6:7], v[90:91], v[18:19]
	v_add_f32_dpp v12, v12, v12 row_half_mirror row_mask:0xf bank_mask:0xf bound_ctrl:1
	v_add_f32_dpp v43, v14, v14 row_half_mirror row_mask:0xf bank_mask:0x5 bound_ctrl:1
	v_pk_fma_f32 v[0:1], v[0:1], v[92:93], v[20:21]
	v_pk_fma_f32 v[2:3], v[2:3], v[94:95], v[22:23]
	v_mul_f32_e32 v12, s8, v12
	v_pk_fma_f32 v[4:5], v[12:13], v[96:97], v[4:5] op_sel_hi:[0,1,1] neg_lo:[1,0,0] neg_hi:[1,0,0]
	v_pk_fma_f32 v[6:7], v[12:13], v[98:99], v[6:7] op_sel_hi:[0,1,1] neg_lo:[1,0,0] neg_hi:[1,0,0]
	v_pk_fma_f32 v[0:1], v[12:13], v[100:101], v[0:1] op_sel_hi:[0,1,1] neg_lo:[1,0,0] neg_hi:[1,0,0]
	v_pk_fma_f32 v[2:3], v[12:13], v[102:103], v[2:3] op_sel_hi:[0,1,1] neg_lo:[1,0,0] neg_hi:[1,0,0]
	s_waitcnt lgkmcnt(0)
; __device__ __forceinline__ void scan_half(const Params& p, LAS unsigned char* lds, int pi, int rh, int pass) {
;     ...
;                 for (int s = 0; s < 32; ++s) {
;                     const int c = s & 1, pc = c ^ 1;
;                     const float si = __int_as_float(__builtin_amdgcn_readlane(__float_as_int(inv2), s));
;                     f32x2 px, py, t01, t23, t45, t67; float x;
;                     f32x2 vv2; vv2.x = Rv[c]; asm volatile("" : "+v"(vv2));
;                     if (s >= 1) {
;                         VPKMUL(px, P01, Rkk[c][0].xy); VPKMUL(py, P01, Rr[pc][0].xy); VPKFMA(px, P23, Rkk[c][0].zw, px); VPKFMA(py, P23, Rr[pc][0].zw, py);
;                         VPKFMA(px, P45, Rkk[c][1].xy, px); VPKFMA(py, P45, Rr[pc][1].xy, py); VPKFMA(px, P67, Rkk[c][1].zw, px); VPKFMA(py, P67, Rr[pc][1].zw, py);
;                         VADD(x, px.x, px.y); VADD(yp, py.x, py.y);
;                     } else {
;                         VPKMUL(px, P01, Rkk[c][0].xy); VPKFMA(px, P23, Rkk[c][0].zw, px); VPKFMA(px, P45, Rkk[c][1].xy, px); VPKFMA(px, P67, Rkk[c][1].zw, px);
;                         VADD(x, px.x, px.y);
;                     }
;                     asm volatile("" ::: "memory");
;                     if (s + 1 < 32) LOADREC((s + 1) & 1, s + 1);
;                     asm volatile("" ::: "memory");
;                     VPKMULBL(t01, vv2, Rkm[c][0].xy); VPKMULBL(t23, vv2, Rkm[c][0].zw);
;                     VDPP1(x); if (s >= 1) VDPP1(yp);
;                     VPKMULBL(t45, vv2, Rkm[c][1].xy); VPKMULBL(t67, vv2, Rkm[c][1].zw);
;                     VDPP2(x); if (s >= 1) VDPP2(yp);
;                     VPKFMA(P01, P01, Rw[c][0].xy, t01); VPKFMA(P23, P23, Rw[c][0].zw, t23);
;                     VDPP3(x); if (s >= 1) VDPP3(yp);
;                     VPKFMA(P45, P45, Rw[c][1].xy, t45); VPKFMA(P67, P67, Rw[c][1].zw, t67);
;                     if (s >= 1) { if (s - 1 < 8) YSHIFT(yk0); else if (s - 1 < 16) YSHIFT(yk1); else if (s - 1 < 24) YSHIFT(yk2); else YSHIFT(yk3); }
;                     x = x * si;
;                     f32x2 x2; x2.x = x; asm volatile("" : "+v"(x2));
;                     VPKNFMABL(P01, x2, Rka[c][0].xy, P01); VPKNFMABL(P23, x2, Rka[c][0].zw, P23); VPKNFMABL(P45, x2, Rka[c][1].xy, P45); VPKNFMABL(P67, x2, Rka[c][1].zw, P67);
;                 }
	ds_read_b128 v[80:83], v35 offset:2448
	ds_read_b128 v[84:87], v35 offset:2464
	ds_read_b128 v[104:107], v35 offset:28560
	ds_read_b128 v[108:111], v35 offset:28576
	ds_read_b32 v148, v36 offset:1152
	ds_read_b128 v[88:91], v35 offset:11152
	ds_read_b128 v[92:95], v35 offset:11168
	ds_read_b128 v[96:99], v35 offset:19856
	ds_read_b128 v[100:103], v35 offset:19872
	ds_read_b128 v[114:117], v35 offset:37264
	ds_read_b128 v[118:121], v35 offset:37280
	v_pk_mul_f32 v[8:9], v[4:5], v[48:49]
	v_pk_mul_f32 v[10:11], v[4:5], v[122:123]
	v_pk_fma_f32 v[8:9], v[6:7], v[50:51], v[8:9]
	v_pk_fma_f32 v[10:11], v[6:7], v[124:125], v[10:11]
	v_pk_fma_f32 v[8:9], v[0:1], v[52:53], v[8:9]
	v_pk_fma_f32 v[10:11], v[0:1], v[126:127], v[10:11]
	v_pk_fma_f32 v[8:9], v[2:3], v[54:55], v[8:9]
	v_pk_fma_f32 v[10:11], v[2:3], v[128:129], v[10:11]
	v_add_f32_e32 v12, v8, v9
	v_add_f32_e32 v14, v10, v11
	v_readlane_b32 s8, v34, 8
	v_pk_mul_f32 v[16:17], v[146:147], v[72:73] op_sel_hi:[0,1]
	v_pk_mul_f32 v[18:19], v[146:147], v[74:75] op_sel_hi:[0,1]
	v_add_f32_dpp v12, v12, v12 quad_perm:[1,0,3,2] row_mask:0xf bank_mask:0xf bound_ctrl:1
	v_add_f32_dpp v14, v14, v14 quad_perm:[1,0,3,2] row_mask:0xf bank_mask:0xf bound_ctrl:1
	v_pk_mul_f32 v[20:21], v[146:147], v[76:77] op_sel_hi:[0,1]
	v_pk_mul_f32 v[22:23], v[146:147], v[78:79] op_sel_hi:[0,1]
	v_add_f32_dpp v12, v12, v12 quad_perm:[2,3,0,1] row_mask:0xf bank_mask:0xf bound_ctrl:1
	v_add_f32_dpp v14, v14, v14 quad_perm:[2,3,0,1] row_mask:0xf bank_mask:0xf bound_ctrl:1
	v_pk_fma_f32 v[4:5], v[4:5], v[56:57], v[16:17]
	v_pk_fma_f32 v[6:7], v[6:7], v[58:59], v[18:19]
	v_add_f32_dpp v12, v12, v12 row_half_mirror row_mask:0xf bank_mask:0xf bound_ctrl:1
	v_add_f32_dpp v43, v14, v14 row_half_mirror row_mask:0xf bank_mask:0xa bound_ctrl:1
	v_pk_fma_f32 v[0:1], v[0:1], v[60:61], v[20:21]
	v_pk_fma_f32 v[2:3], v[2:3], v[62:63], v[22:23]
	v_mul_f32_e32 v12, s8, v12
	v_pk_fma_f32 v[4:5], v[12:13], v[64:65], v[4:5] op_sel_hi:[0,1,1] neg_lo:[1,0,0] neg_hi:[1,0,0]
	v_pk_fma_f32 v[6:7], v[12:13], v[66:67], v[6:7] op_sel_hi:[0,1,1] neg_lo:[1,0,0] neg_hi:[1,0,0]
	v_pk_fma_f32 v[0:1], v[12:13], v[68:69], v[0:1] op_sel_hi:[0,1,1] neg_lo:[1,0,0] neg_hi:[1,0,0]
	v_pk_fma_f32 v[2:3], v[12:13], v[70:71], v[2:3] op_sel_hi:[0,1,1] neg_lo:[1,0,0] neg_hi:[1,0,0]
	s_waitcnt lgkmcnt(0)
	ds_read_b128 v[48:51], v35 offset:2720
	ds_read_b128 v[52:55], v35 offset:2736
	ds_read_b128 v[72:75], v35 offset:28832
	ds_read_b128 v[76:79], v35 offset:28848
	ds_read_b32 v146, v36 offset:1280
	ds_read_b128 v[56:59], v35 offset:11424
	ds_read_b128 v[60:63], v35 offset:11440
	ds_read_b128 v[64:67], v35 offset:20128
	ds_read_b128 v[68:71], v35 offset:20144
	ds_read_b128 v[122:125], v35 offset:37536
	ds_read_b128 v[126:129], v35 offset:37552
	v_pk_mul_f32 v[8:9], v[4:5], v[80:81]
	v_pk_mul_f32 v[10:11], v[4:5], v[138:139]
	v_pk_fma_f32 v[8:9], v[6:7], v[82:83], v[8:9]
	v_pk_fma_f32 v[10:11], v[6:7], v[140:141], v[10:11]
	v_pk_fma_f32 v[8:9], v[0:1], v[84:85], v[8:9]
	v_pk_fma_f32 v[10:11], v[0:1], v[142:143], v[10:11]
	v_pk_fma_f32 v[8:9], v[2:3], v[86:87], v[8:9]
	v_pk_fma_f32 v[10:11], v[2:3], v[144:145], v[10:11]
	v_add_f32_e32 v12, v8, v9
	v_add_f32_e32 v14, v10, v11
	v_readlane_b32 s8, v34, 9
	v_pk_mul_f32 v[16:17], v[148:149], v[104:105] op_sel_hi:[0,1]
	v_pk_mul_f32 v[18:19], v[148:149], v[106:107] op_sel_hi:[0,1]
	v_add_f32_dpp v12, v12, v12 quad_perm:[1,0,3,2] row_mask:0xf bank_mask:0xf bound_ctrl:1
	v_add_f32_dpp v14, v14, v14 quad_perm:[1,0,3,2] row_mask:0xf bank_mask:0xf bound_ctrl:1
	v_pk_mul_f32 v[20:21], v[148:149], v[108:109] op_sel_hi:[0,1]
	v_pk_mul_f32 v[22:23], v[148:149], v[110:111] op_sel_hi:[0,1]
	v_add_f32_dpp v12, v12, v12 quad_perm:[2,3,0,1] row_mask:0xf bank_mask:0xf bound_ctrl:1
	v_add_f32_dpp v14, v14, v14 quad_perm:[2,3,0,1] row_mask:0xf bank_mask:0xf bound_ctrl:1
	v_pk_fma_f32 v[4:5], v[4:5], v[88:89], v[16:17]
	v_pk_fma_f32 v[6:7], v[6:7], v[90:91], v[18:19]
	v_add_f32_dpp v12, v12, v12 row_half_mirror row_mask:0xf bank_mask:0xf bound_ctrl:1
	v_add_f32_dpp v44, v14, v14 row_half_mirror row_mask:0xf bank_mask:0x5 bound_ctrl:1
	v_pk_fma_f32 v[0:1], v[0:1], v[92:93], v[20:21]
	v_pk_fma_f32 v[2:3], v[2:3], v[94:95], v[22:23]
	v_mul_f32_e32 v12, s8, v12
	v_pk_fma_f32 v[4:5], v[12:13], v[96:97], v[4:5] op_sel_hi:[0,1,1] neg_lo:[1,0,0] neg_hi:[1,0,0]
	v_pk_fma_f32 v[6:7], v[12:13], v[98:99], v[6:7] op_sel_hi:[0,1,1] neg_lo:[1,0,0] neg_hi:[1,0,0]
	v_pk_fma_f32 v[0:1], v[12:13], v[100:101], v[0:1] op_sel_hi:[0,1,1] neg_lo:[1,0,0] neg_hi:[1,0,0]
	v_pk_fma_f32 v[2:3], v[12:13], v[102:103], v[2:3] op_sel_hi:[0,1,1] neg_lo:[1,0,0] neg_hi:[1,0,0]
	s_waitcnt lgkmcnt(0)
; __device__ __forceinline__ void scan_half(const Params& p, LAS unsigned char* lds, int pi, int rh, int pass) {
;     ...
;                 for (int s = 0; s < 32; ++s) {
;                     const int c = s & 1, pc = c ^ 1;
;                     const float si = __int_as_float(__builtin_amdgcn_readlane(__float_as_int(inv2), s));
;                     f32x2 px, py, t01, t23, t45, t67; float x;
;                     f32x2 vv2; vv2.x = Rv[c]; asm volatile("" : "+v"(vv2));
;                     if (s >= 1) {
;                         VPKMUL(px, P01, Rkk[c][0].xy); VPKMUL(py, P01, Rr[pc][0].xy); VPKFMA(px, P23, Rkk[c][0].zw, px); VPKFMA(py, P23, Rr[pc][0].zw, py);
;                         VPKFMA(px, P45, Rkk[c][1].xy, px); VPKFMA(py, P45, Rr[pc][1].xy, py); VPKFMA(px, P67, Rkk[c][1].zw, px); VPKFMA(py, P67, Rr[pc][1].zw, py);
;                         VADD(x, px.x, px.y); VADD(yp, py.x, py.y);
;                     } else {
;                         VPKMUL(px, P01, Rkk[c][0].xy); VPKFMA(px, P23, Rkk[c][0].zw, px); VPKFMA(px, P45, Rkk[c][1].xy, px); VPKFMA(px, P67, Rkk[c][1].zw, px);
;                         VADD(x, px.x, px.y);
;                     }
;                     asm volatile("" ::: "memory");
;                     if (s + 1 < 32) LOADREC((s + 1) & 1, s + 1);
;                     asm volatile("" ::: "memory");
;                     VPKMULBL(t01, vv2, Rkm[c][0].xy); VPKMULBL(t23, vv2, Rkm[c][0].zw);
;                     VDPP1(x); if (s >= 1) VDPP1(yp);
;                     VPKMULBL(t45, vv2, Rkm[c][1].xy); VPKMULBL(t67, vv2, Rkm[c][1].zw);
;                     VDPP2(x); if (s >= 1) VDPP2(yp);
;                     VPKFMA(P01, P01, Rw[c][0].xy, t01); VPKFMA(P23, P23, Rw[c][0].zw, t23);
;                     VDPP3(x); if (s >= 1) VDPP3(yp);
;                     VPKFMA(P45, P45, Rw[c][1].xy, t45); VPKFMA(P67, P67, Rw[c][1].zw, t67);
;                     if (s >= 1) { if (s - 1 < 8) YSHIFT(yk0); else if (s - 1 < 16) YSHIFT(yk1); else if (s - 1 < 24) YSHIFT(yk2); else YSHIFT(yk3); }
;                     x = x * si;
;                     f32x2 x2; x2.x = x; asm volatile("" : "+v"(x2));
;                     VPKNFMABL(P01, x2, Rka[c][0].xy, P01); VPKNFMABL(P23, x2, Rka[c][0].zw, P23); VPKNFMABL(P45, x2, Rka[c][1].xy, P45); VPKNFMABL(P67, x2, Rka[c][1].zw, P67);
;                 }
	ds_read_b128 v[80:83], v35 offset:2992
	ds_read_b128 v[84:87], v35 offset:3008
	ds_read_b128 v[104:107], v35 offset:29104
	ds_read_b128 v[108:111], v35 offset:29120
	ds_read_b32 v148, v36 offset:1408
	ds_read_b128 v[88:91], v35 offset:11696
	ds_read_b128 v[92:95], v35 offset:11712
	ds_read_b128 v[96:99], v35 offset:20400
	ds_read_b128 v[100:103], v35 offset:20416
	ds_read_b128 v[138:141], v35 offset:37808
	ds_read_b128 v[142:145], v35 offset:37824
	v_pk_mul_f32 v[8:9], v[4:5], v[48:49]
	v_pk_mul_f32 v[10:11], v[4:5], v[114:115]
	v_pk_fma_f32 v[8:9], v[6:7], v[50:51], v[8:9]
	v_pk_fma_f32 v[10:11], v[6:7], v[116:117], v[10:11]
	v_pk_fma_f32 v[8:9], v[0:1], v[52:53], v[8:9]
	v_pk_fma_f32 v[10:11], v[0:1], v[118:119], v[10:11]
	v_pk_fma_f32 v[8:9], v[2:3], v[54:55], v[8:9]
	v_pk_fma_f32 v[10:11], v[2:3], v[120:121], v[10:11]
	v_add_f32_e32 v12, v8, v9
	v_add_f32_e32 v14, v10, v11
	v_readlane_b32 s8, v34, 10
	v_pk_mul_f32 v[16:17], v[146:147], v[72:73] op_sel_hi:[0,1]
	v_pk_mul_f32 v[18:19], v[146:147], v[74:75] op_sel_hi:[0,1]
	v_add_f32_dpp v12, v12, v12 quad_perm:[1,0,3,2] row_mask:0xf bank_mask:0xf bound_ctrl:1
	v_add_f32_dpp v14, v14, v14 quad_perm:[1,0,3,2] row_mask:0xf bank_mask:0xf bound_ctrl:1
	v_pk_mul_f32 v[20:21], v[146:147], v[76:77] op_sel_hi:[0,1]
	v_pk_mul_f32 v[22:23], v[146:147], v[78:79] op_sel_hi:[0,1]
	v_add_f32_dpp v12, v12, v12 quad_perm:[2,3,0,1] row_mask:0xf bank_mask:0xf bound_ctrl:1
	v_add_f32_dpp v14, v14, v14 quad_perm:[2,3,0,1] row_mask:0xf bank_mask:0xf bound_ctrl:1
	v_pk_fma_f32 v[4:5], v[4:5], v[56:57], v[16:17]
	v_pk_fma_f32 v[6:7], v[6:7], v[58:59], v[18:19]
	v_add_f32_dpp v12, v12, v12 row_half_mirror row_mask:0xf bank_mask:0xf bound_ctrl:1
	v_add_f32_dpp v44, v14, v14 row_half_mirror row_mask:0xf bank_mask:0xa bound_ctrl:1
	v_pk_fma_f32 v[0:1], v[0:1], v[60:61], v[20:21]
	v_pk_fma_f32 v[2:3], v[2:3], v[62:63], v[22:23]
	v_mul_f32_e32 v12, s8, v12
	v_pk_fma_f32 v[4:5], v[12:13], v[64:65], v[4:5] op_sel_hi:[0,1,1] neg_lo:[1,0,0] neg_hi:[1,0,0]
	v_pk_fma_f32 v[6:7], v[12:13], v[66:67], v[6:7] op_sel_hi:[0,1,1] neg_lo:[1,0,0] neg_hi:[1,0,0]
	v_pk_fma_f32 v[0:1], v[12:13], v[68:69], v[0:1] op_sel_hi:[0,1,1] neg_lo:[1,0,0] neg_hi:[1,0,0]
	v_pk_fma_f32 v[2:3], v[12:13], v[70:71], v[2:3] op_sel_hi:[0,1,1] neg_lo:[1,0,0] neg_hi:[1,0,0]
	s_waitcnt lgkmcnt(0)
	ds_read_b128 v[48:51], v35 offset:3264
	ds_read_b128 v[52:55], v35 offset:3280
	ds_read_b128 v[72:75], v35 offset:29376
	ds_read_b128 v[76:79], v35 offset:29392
	ds_read_b32 v146, v36 offset:1536
	ds_read_b128 v[56:59], v35 offset:11968
	ds_read_b128 v[60:63], v35 offset:11984
	ds_read_b128 v[64:67], v35 offset:20672
	ds_read_b128 v[68:71], v35 offset:20688
	ds_read_b128 v[114:117], v35 offset:38080
	ds_read_b128 v[118:121], v35 offset:38096
	v_pk_mul_f32 v[8:9], v[4:5], v[80:81]
	v_pk_mul_f32 v[10:11], v[4:5], v[122:123]
	v_pk_fma_f32 v[8:9], v[6:7], v[82:83], v[8:9]
	v_pk_fma_f32 v[10:11], v[6:7], v[124:125], v[10:11]
	v_pk_fma_f32 v[8:9], v[0:1], v[84:85], v[8:9]
	v_pk_fma_f32 v[10:11], v[0:1], v[126:127], v[10:11]
	v_pk_fma_f32 v[8:9], v[2:3], v[86:87], v[8:9]
	v_pk_fma_f32 v[10:11], v[2:3], v[128:129], v[10:11]
	v_add_f32_e32 v12, v8, v9
	v_add_f32_e32 v14, v10, v11
	v_readlane_b32 s8, v34, 11
	v_pk_mul_f32 v[16:17], v[148:149], v[104:105] op_sel_hi:[0,1]
	v_pk_mul_f32 v[18:19], v[148:149], v[106:107] op_sel_hi:[0,1]
	v_add_f32_dpp v12, v12, v12 quad_perm:[1,0,3,2] row_mask:0xf bank_mask:0xf bound_ctrl:1
	v_add_f32_dpp v14, v14, v14 quad_perm:[1,0,3,2] row_mask:0xf bank_mask:0xf bound_ctrl:1
	v_pk_mul_f32 v[20:21], v[148:149], v[108:109] op_sel_hi:[0,1]
	v_pk_mul_f32 v[22:23], v[148:149], v[110:111] op_sel_hi:[0,1]
	v_add_f32_dpp v12, v12, v12 quad_perm:[2,3,0,1] row_mask:0xf bank_mask:0xf bound_ctrl:1
	v_add_f32_dpp v14, v14, v14 quad_perm:[2,3,0,1] row_mask:0xf bank_mask:0xf bound_ctrl:1
	v_pk_fma_f32 v[4:5], v[4:5], v[88:89], v[16:17]
	v_pk_fma_f32 v[6:7], v[6:7], v[90:91], v[18:19]
	v_add_f32_dpp v12, v12, v12 row_half_mirror row_mask:0xf bank_mask:0xf bound_ctrl:1
	v_add_f32_dpp v45, v14, v14 row_half_mirror row_mask:0xf bank_mask:0x5 bound_ctrl:1
	v_pk_fma_f32 v[0:1], v[0:1], v[92:93], v[20:21]
	v_pk_fma_f32 v[2:3], v[2:3], v[94:95], v[22:23]
	v_mul_f32_e32 v12, s8, v12
	v_pk_fma_f32 v[4:5], v[12:13], v[96:97], v[4:5] op_sel_hi:[0,1,1] neg_lo:[1,0,0] neg_hi:[1,0,0]
	v_pk_fma_f32 v[6:7], v[12:13], v[98:99], v[6:7] op_sel_hi:[0,1,1] neg_lo:[1,0,0] neg_hi:[1,0,0]
	v_pk_fma_f32 v[0:1], v[12:13], v[100:101], v[0:1] op_sel_hi:[0,1,1] neg_lo:[1,0,0] neg_hi:[1,0,0]
	v_pk_fma_f32 v[2:3], v[12:13], v[102:103], v[2:3] op_sel_hi:[0,1,1] neg_lo:[1,0,0] neg_hi:[1,0,0]
	s_waitcnt lgkmcnt(0)
; __device__ __forceinline__ void scan_half(const Params& p, LAS unsigned char* lds, int pi, int rh, int pass) {
;     ...
;                 for (int s = 0; s < 32; ++s) {
;                     const int c = s & 1, pc = c ^ 1;
;                     const float si = __int_as_float(__builtin_amdgcn_readlane(__float_as_int(inv2), s));
;                     f32x2 px, py, t01, t23, t45, t67; float x;
;                     f32x2 vv2; vv2.x = Rv[c]; asm volatile("" : "+v"(vv2));
;                     if (s >= 1) {
;                         VPKMUL(px, P01, Rkk[c][0].xy); VPKMUL(py, P01, Rr[pc][0].xy); VPKFMA(px, P23, Rkk[c][0].zw, px); VPKFMA(py, P23, Rr[pc][0].zw, py);
;                         VPKFMA(px, P45, Rkk[c][1].xy, px); VPKFMA(py, P45, Rr[pc][1].xy, py); VPKFMA(px, P67, Rkk[c][1].zw, px); VPKFMA(py, P67, Rr[pc][1].zw, py);
;                         VADD(x, px.x, px.y); VADD(yp, py.x, py.y);
;                     } else {
;                         VPKMUL(px, P01, Rkk[c][0].xy); VPKFMA(px, P23, Rkk[c][0].zw, px); VPKFMA(px, P45, Rkk[c][1].xy, px); VPKFMA(px, P67, Rkk[c][1].zw, px);
;                         VADD(x, px.x, px.y);
;                     }
;                     asm volatile("" ::: "memory");
;                     if (s + 1 < 32) LOADREC((s + 1) & 1, s + 1);
;                     asm volatile("" ::: "memory");
;                     VPKMULBL(t01, vv2, Rkm[c][0].xy); VPKMULBL(t23, vv2, Rkm[c][0].zw);
;                     VDPP1(x); if (s >= 1) VDPP1(yp);
;                     VPKMULBL(t45, vv2, Rkm[c][1].xy); VPKMULBL(t67, vv2, Rkm[c][1].zw);
;                     VDPP2(x); if (s >= 1) VDPP2(yp);
;                     VPKFMA(P01, P01, Rw[c][0].xy, t01); VPKFMA(P23, P23, Rw[c][0].zw, t23);
;                     VDPP3(x); if (s >= 1) VDPP3(yp);
;                     VPKFMA(P45, P45, Rw[c][1].xy, t45); VPKFMA(P67, P67, Rw[c][1].zw, t67);
;                     if (s >= 1) { if (s - 1 < 8) YSHIFT(yk0); else if (s - 1 < 16) YSHIFT(yk1); else if (s - 1 < 24) YSHIFT(yk2); else YSHIFT(yk3); }
;                     x = x * si;
;                     f32x2 x2; x2.x = x; asm volatile("" : "+v"(x2));
;                     VPKNFMABL(P01, x2, Rka[c][0].xy, P01); VPKNFMABL(P23, x2, Rka[c][0].zw, P23); VPKNFMABL(P45, x2, Rka[c][1].xy, P45); VPKNFMABL(P67, x2, Rka[c][1].zw, P67);
;                 }
	ds_read_b128 v[80:83], v35 offset:3536
	ds_read_b128 v[84:87], v35 offset:3552
	ds_read_b128 v[104:107], v35 offset:29648
	ds_read_b128 v[108:111], v35 offset:29664
	ds_read_b32 v148, v36 offset:1664
	ds_read_b128 v[88:91], v35 offset:12240
	ds_read_b128 v[92:95], v35 offset:12256
	ds_read_b128 v[96:99], v35 offset:20944
	ds_read_b128 v[100:103], v35 offset:20960
	ds_read_b128 v[122:125], v35 offset:38352
	ds_read_b128 v[126:129], v35 offset:38368
	v_pk_mul_f32 v[8:9], v[4:5], v[48:49]
	v_pk_mul_f32 v[10:11], v[4:5], v[138:139]
	v_pk_fma_f32 v[8:9], v[6:7], v[50:51], v[8:9]
	v_pk_fma_f32 v[10:11], v[6:7], v[140:141], v[10:11]
	v_pk_fma_f32 v[8:9], v[0:1], v[52:53], v[8:9]
	v_pk_fma_f32 v[10:11], v[0:1], v[142:143], v[10:11]
	v_pk_fma_f32 v[8:9], v[2:3], v[54:55], v[8:9]
	v_pk_fma_f32 v[10:11], v[2:3], v[144:145], v[10:11]
	v_add_f32_e32 v12, v8, v9
	v_add_f32_e32 v14, v10, v11
	v_readlane_b32 s8, v34, 12
	v_pk_mul_f32 v[16:17], v[146:147], v[72:73] op_sel_hi:[0,1]
	v_pk_mul_f32 v[18:19], v[146:147], v[74:75] op_sel_hi:[0,1]
	v_add_f32_dpp v12, v12, v12 quad_perm:[1,0,3,2] row_mask:0xf bank_mask:0xf bound_ctrl:1
	v_add_f32_dpp v14, v14, v14 quad_perm:[1,0,3,2] row_mask:0xf bank_mask:0xf bound_ctrl:1
	v_pk_mul_f32 v[20:21], v[146:147], v[76:77] op_sel_hi:[0,1]
	v_pk_mul_f32 v[22:23], v[146:147], v[78:79] op_sel_hi:[0,1]
	v_add_f32_dpp v12, v12, v12 quad_perm:[2,3,0,1] row_mask:0xf bank_mask:0xf bound_ctrl:1
	v_add_f32_dpp v14, v14, v14 quad_perm:[2,3,0,1] row_mask:0xf bank_mask:0xf bound_ctrl:1
	v_pk_fma_f32 v[4:5], v[4:5], v[56:57], v[16:17]
	v_pk_fma_f32 v[6:7], v[6:7], v[58:59], v[18:19]
	v_add_f32_dpp v12, v12, v12 row_half_mirror row_mask:0xf bank_mask:0xf bound_ctrl:1
	v_add_f32_dpp v45, v14, v14 row_half_mirror row_mask:0xf bank_mask:0xa bound_ctrl:1
	v_pk_fma_f32 v[0:1], v[0:1], v[60:61], v[20:21]
	v_pk_fma_f32 v[2:3], v[2:3], v[62:63], v[22:23]
	v_mul_f32_e32 v12, s8, v12
	v_pk_fma_f32 v[4:5], v[12:13], v[64:65], v[4:5] op_sel_hi:[0,1,1] neg_lo:[1,0,0] neg_hi:[1,0,0]
	v_pk_fma_f32 v[6:7], v[12:13], v[66:67], v[6:7] op_sel_hi:[0,1,1] neg_lo:[1,0,0] neg_hi:[1,0,0]
	v_pk_fma_f32 v[0:1], v[12:13], v[68:69], v[0:1] op_sel_hi:[0,1,1] neg_lo:[1,0,0] neg_hi:[1,0,0]
	v_pk_fma_f32 v[2:3], v[12:13], v[70:71], v[2:3] op_sel_hi:[0,1,1] neg_lo:[1,0,0] neg_hi:[1,0,0]
	s_waitcnt lgkmcnt(0)
	ds_read_b128 v[48:51], v35 offset:3808
	ds_read_b128 v[52:55], v35 offset:3824
	ds_read_b128 v[72:75], v35 offset:29920
	ds_read_b128 v[76:79], v35 offset:29936
	ds_read_b32 v146, v36 offset:1792
	ds_read_b128 v[56:59], v35 offset:12512
	ds_read_b128 v[60:63], v35 offset:12528
	ds_read_b128 v[64:67], v35 offset:21216
	ds_read_b128 v[68:71], v35 offset:21232
	ds_read_b128 v[138:141], v35 offset:38624
	ds_read_b128 v[142:145], v35 offset:38640
	v_pk_mul_f32 v[8:9], v[4:5], v[80:81]
	v_pk_mul_f32 v[10:11], v[4:5], v[114:115]
	v_pk_fma_f32 v[8:9], v[6:7], v[82:83], v[8:9]
	v_pk_fma_f32 v[10:11], v[6:7], v[116:117], v[10:11]
	v_pk_fma_f32 v[8:9], v[0:1], v[84:85], v[8:9]
	v_pk_fma_f32 v[10:11], v[0:1], v[118:119], v[10:11]
	v_pk_fma_f32 v[8:9], v[2:3], v[86:87], v[8:9]
	v_pk_fma_f32 v[10:11], v[2:3], v[120:121], v[10:11]
	v_add_f32_e32 v12, v8, v9
	v_add_f32_e32 v14, v10, v11
	v_readlane_b32 s8, v34, 13
	v_pk_mul_f32 v[16:17], v[148:149], v[104:105] op_sel_hi:[0,1]
	v_pk_mul_f32 v[18:19], v[148:149], v[106:107] op_sel_hi:[0,1]
	v_add_f32_dpp v12, v12, v12 quad_perm:[1,0,3,2] row_mask:0xf bank_mask:0xf bound_ctrl:1
	v_add_f32_dpp v14, v14, v14 quad_perm:[1,0,3,2] row_mask:0xf bank_mask:0xf bound_ctrl:1
	v_pk_mul_f32 v[20:21], v[148:149], v[108:109] op_sel_hi:[0,1]
	v_pk_mul_f32 v[22:23], v[148:149], v[110:111] op_sel_hi:[0,1]
	v_add_f32_dpp v12, v12, v12 quad_perm:[2,3,0,1] row_mask:0xf bank_mask:0xf bound_ctrl:1
	v_add_f32_dpp v14, v14, v14 quad_perm:[2,3,0,1] row_mask:0xf bank_mask:0xf bound_ctrl:1
	v_pk_fma_f32 v[4:5], v[4:5], v[88:89], v[16:17]
	v_pk_fma_f32 v[6:7], v[6:7], v[90:91], v[18:19]
	v_add_f32_dpp v12, v12, v12 row_half_mirror row_mask:0xf bank_mask:0xf bound_ctrl:1
	v_add_f32_dpp v46, v14, v14 row_half_mirror row_mask:0xf bank_mask:0x5 bound_ctrl:1
	v_pk_fma_f32 v[0:1], v[0:1], v[92:93], v[20:21]
	v_pk_fma_f32 v[2:3], v[2:3], v[94:95], v[22:23]
	v_mul_f32_e32 v12, s8, v12
	v_pk_fma_f32 v[4:5], v[12:13], v[96:97], v[4:5] op_sel_hi:[0,1,1] neg_lo:[1,0,0] neg_hi:[1,0,0]
	v_pk_fma_f32 v[6:7], v[12:13], v[98:99], v[6:7] op_sel_hi:[0,1,1] neg_lo:[1,0,0] neg_hi:[1,0,0]
	v_pk_fma_f32 v[0:1], v[12:13], v[100:101], v[0:1] op_sel_hi:[0,1,1] neg_lo:[1,0,0] neg_hi:[1,0,0]
	v_pk_fma_f32 v[2:3], v[12:13], v[102:103], v[2:3] op_sel_hi:[0,1,1] neg_lo:[1,0,0] neg_hi:[1,0,0]
	s_waitcnt lgkmcnt(0)
; __device__ __forceinline__ void scan_half(const Params& p, LAS unsigned char* lds, int pi, int rh, int pass) {
;     ...
;                 for (int s = 0; s < 32; ++s) {
;                     const int c = s & 1, pc = c ^ 1;
;                     const float si = __int_as_float(__builtin_amdgcn_readlane(__float_as_int(inv2), s));
;                     f32x2 px, py, t01, t23, t45, t67; float x;
;                     f32x2 vv2; vv2.x = Rv[c]; asm volatile("" : "+v"(vv2));
;                     if (s >= 1) {
;                         VPKMUL(px, P01, Rkk[c][0].xy); VPKMUL(py, P01, Rr[pc][0].xy); VPKFMA(px, P23, Rkk[c][0].zw, px); VPKFMA(py, P23, Rr[pc][0].zw, py);
;                         VPKFMA(px, P45, Rkk[c][1].xy, px); VPKFMA(py, P45, Rr[pc][1].xy, py); VPKFMA(px, P67, Rkk[c][1].zw, px); VPKFMA(py, P67, Rr[pc][1].zw, py);
;                         VADD(x, px.x, px.y); VADD(yp, py.x, py.y);
;                     } else {
;                         VPKMUL(px, P01, Rkk[c][0].xy); VPKFMA(px, P23, Rkk[c][0].zw, px); VPKFMA(px, P45, Rkk[c][1].xy, px); VPKFMA(px, P67, Rkk[c][1].zw, px);
;                         VADD(x, px.x, px.y);
;                     }
;                     asm volatile("" ::: "memory");
;                     if (s + 1 < 32) LOADREC((s + 1) & 1, s + 1);
;                     asm volatile("" ::: "memory");
;                     VPKMULBL(t01, vv2, Rkm[c][0].xy); VPKMULBL(t23, vv2, Rkm[c][0].zw);
;                     VDPP1(x); if (s >= 1) VDPP1(yp);
;                     VPKMULBL(t45, vv2, Rkm[c][1].xy); VPKMULBL(t67, vv2, Rkm[c][1].zw);
;                     VDPP2(x); if (s >= 1) VDPP2(yp);
;                     VPKFMA(P01, P01, Rw[c][0].xy, t01); VPKFMA(P23, P23, Rw[c][0].zw, t23);
;                     VDPP3(x); if (s >= 1) VDPP3(yp);
;                     VPKFMA(P45, P45, Rw[c][1].xy, t45); VPKFMA(P67, P67, Rw[c][1].zw, t67);
;                     if (s >= 1) { if (s - 1 < 8) YSHIFT(yk0); else if (s - 1 < 16) YSHIFT(yk1); else if (s - 1 < 24) YSHIFT(yk2); else YSHIFT(yk3); }
;                     x = x * si;
;                     f32x2 x2; x2.x = x; asm volatile("" : "+v"(x2));
;                     VPKNFMABL(P01, x2, Rka[c][0].xy, P01); VPKNFMABL(P23, x2, Rka[c][0].zw, P23); VPKNFMABL(P45, x2, Rka[c][1].xy, P45); VPKNFMABL(P67, x2, Rka[c][1].zw, P67);
;                 }
	ds_read_b128 v[80:83], v35 offset:4080
	ds_read_b128 v[84:87], v35 offset:4096
	ds_read_b128 v[104:107], v35 offset:30192
	ds_read_b128 v[108:111], v35 offset:30208
	ds_read_b32 v148, v36 offset:1920
	ds_read_b128 v[88:91], v35 offset:12784
	ds_read_b128 v[92:95], v35 offset:12800
	ds_read_b128 v[96:99], v35 offset:21488
	ds_read_b128 v[100:103], v35 offset:21504
	ds_read_b128 v[114:117], v35 offset:38896
	ds_read_b128 v[118:121], v35 offset:38912
	v_pk_mul_f32 v[8:9], v[4:5], v[48:49]
	v_pk_mul_f32 v[10:11], v[4:5], v[122:123]
	v_pk_fma_f32 v[8:9], v[6:7], v[50:51], v[8:9]
	v_pk_fma_f32 v[10:11], v[6:7], v[124:125], v[10:11]
	v_pk_fma_f32 v[8:9], v[0:1], v[52:53], v[8:9]
	v_pk_fma_f32 v[10:11], v[0:1], v[126:127], v[10:11]
	v_pk_fma_f32 v[8:9], v[2:3], v[54:55], v[8:9]
	v_pk_fma_f32 v[10:11], v[2:3], v[128:129], v[10:11]
	v_add_f32_e32 v12, v8, v9
	v_add_f32_e32 v14, v10, v11
	v_readlane_b32 s8, v34, 14
	v_pk_mul_f32 v[16:17], v[146:147], v[72:73] op_sel_hi:[0,1]
	v_pk_mul_f32 v[18:19], v[146:147], v[74:75] op_sel_hi:[0,1]
	v_add_f32_dpp v12, v12, v12 quad_perm:[1,0,3,2] row_mask:0xf bank_mask:0xf bound_ctrl:1
	v_add_f32_dpp v14, v14, v14 quad_perm:[1,0,3,2] row_mask:0xf bank_mask:0xf bound_ctrl:1
	v_pk_mul_f32 v[20:21], v[146:147], v[76:77] op_sel_hi:[0,1]
	v_pk_mul_f32 v[22:23], v[146:147], v[78:79] op_sel_hi:[0,1]
	v_add_f32_dpp v12, v12, v12 quad_perm:[2,3,0,1] row_mask:0xf bank_mask:0xf bound_ctrl:1
	v_add_f32_dpp v14, v14, v14 quad_perm:[2,3,0,1] row_mask:0xf bank_mask:0xf bound_ctrl:1
	v_pk_fma_f32 v[4:5], v[4:5], v[56:57], v[16:17]
	v_pk_fma_f32 v[6:7], v[6:7], v[58:59], v[18:19]
	v_add_f32_dpp v12, v12, v12 row_half_mirror row_mask:0xf bank_mask:0xf bound_ctrl:1
	v_add_f32_dpp v46, v14, v14 row_half_mirror row_mask:0xf bank_mask:0xa bound_ctrl:1
	v_pk_fma_f32 v[0:1], v[0:1], v[60:61], v[20:21]
	v_pk_fma_f32 v[2:3], v[2:3], v[62:63], v[22:23]
	v_mul_f32_e32 v12, s8, v12
	v_pk_fma_f32 v[4:5], v[12:13], v[64:65], v[4:5] op_sel_hi:[0,1,1] neg_lo:[1,0,0] neg_hi:[1,0,0]
	v_pk_fma_f32 v[6:7], v[12:13], v[66:67], v[6:7] op_sel_hi:[0,1,1] neg_lo:[1,0,0] neg_hi:[1,0,0]
	v_pk_fma_f32 v[0:1], v[12:13], v[68:69], v[0:1] op_sel_hi:[0,1,1] neg_lo:[1,0,0] neg_hi:[1,0,0]
	v_pk_fma_f32 v[2:3], v[12:13], v[70:71], v[2:3] op_sel_hi:[0,1,1] neg_lo:[1,0,0] neg_hi:[1,0,0]
	s_waitcnt lgkmcnt(0)
	ds_read_b128 v[48:51], v35 offset:4352
	ds_read_b128 v[52:55], v35 offset:4368
	ds_read_b128 v[72:75], v35 offset:30464
	ds_read_b128 v[76:79], v35 offset:30480
	ds_read_b32 v146, v36 offset:2048
	ds_read_b128 v[56:59], v35 offset:13056
	ds_read_b128 v[60:63], v35 offset:13072
	ds_read_b128 v[64:67], v35 offset:21760
	ds_read_b128 v[68:71], v35 offset:21776
	ds_read_b128 v[122:125], v35 offset:39168
	ds_read_b128 v[126:129], v35 offset:39184
	v_pk_mul_f32 v[8:9], v[4:5], v[80:81]
	v_pk_mul_f32 v[10:11], v[4:5], v[138:139]
	v_pk_fma_f32 v[8:9], v[6:7], v[82:83], v[8:9]
	v_pk_fma_f32 v[10:11], v[6:7], v[140:141], v[10:11]
	v_pk_fma_f32 v[8:9], v[0:1], v[84:85], v[8:9]
	v_pk_fma_f32 v[10:11], v[0:1], v[142:143], v[10:11]
	v_pk_fma_f32 v[8:9], v[2:3], v[86:87], v[8:9]
	v_pk_fma_f32 v[10:11], v[2:3], v[144:145], v[10:11]
	v_add_f32_e32 v12, v8, v9
	v_add_f32_e32 v14, v10, v11
	v_readlane_b32 s8, v34, 15
	v_pk_mul_f32 v[16:17], v[148:149], v[104:105] op_sel_hi:[0,1]
	v_pk_mul_f32 v[18:19], v[148:149], v[106:107] op_sel_hi:[0,1]
	v_add_f32_dpp v12, v12, v12 quad_perm:[1,0,3,2] row_mask:0xf bank_mask:0xf bound_ctrl:1
	v_add_f32_dpp v14, v14, v14 quad_perm:[1,0,3,2] row_mask:0xf bank_mask:0xf bound_ctrl:1
	v_pk_mul_f32 v[20:21], v[148:149], v[108:109] op_sel_hi:[0,1]
	v_pk_mul_f32 v[22:23], v[148:149], v[110:111] op_sel_hi:[0,1]
	v_add_f32_dpp v12, v12, v12 quad_perm:[2,3,0,1] row_mask:0xf bank_mask:0xf bound_ctrl:1
	v_add_f32_dpp v14, v14, v14 quad_perm:[2,3,0,1] row_mask:0xf bank_mask:0xf bound_ctrl:1
	v_pk_fma_f32 v[4:5], v[4:5], v[88:89], v[16:17]
	v_pk_fma_f32 v[6:7], v[6:7], v[90:91], v[18:19]
	v_add_f32_dpp v12, v12, v12 row_half_mirror row_mask:0xf bank_mask:0xf bound_ctrl:1
	v_add_f32_dpp v47, v14, v14 row_half_mirror row_mask:0xf bank_mask:0x5 bound_ctrl:1
	v_pk_fma_f32 v[0:1], v[0:1], v[92:93], v[20:21]
	v_pk_fma_f32 v[2:3], v[2:3], v[94:95], v[22:23]
	v_mul_f32_e32 v12, s8, v12
	v_pk_fma_f32 v[4:5], v[12:13], v[96:97], v[4:5] op_sel_hi:[0,1,1] neg_lo:[1,0,0] neg_hi:[1,0,0]
	v_pk_fma_f32 v[6:7], v[12:13], v[98:99], v[6:7] op_sel_hi:[0,1,1] neg_lo:[1,0,0] neg_hi:[1,0,0]
	v_pk_fma_f32 v[0:1], v[12:13], v[100:101], v[0:1] op_sel_hi:[0,1,1] neg_lo:[1,0,0] neg_hi:[1,0,0]
	v_pk_fma_f32 v[2:3], v[12:13], v[102:103], v[2:3] op_sel_hi:[0,1,1] neg_lo:[1,0,0] neg_hi:[1,0,0]
	s_waitcnt lgkmcnt(0)
; __device__ __forceinline__ void scan_half(const Params& p, LAS unsigned char* lds, int pi, int rh, int pass) {
;     ...
;                 for (int s = 0; s < 32; ++s) {
;                     const int c = s & 1, pc = c ^ 1;
;                     const float si = __int_as_float(__builtin_amdgcn_readlane(__float_as_int(inv2), s));
;                     f32x2 px, py, t01, t23, t45, t67; float x;
;                     f32x2 vv2; vv2.x = Rv[c]; asm volatile("" : "+v"(vv2));
;                     if (s >= 1) {
;                         VPKMUL(px, P01, Rkk[c][0].xy); VPKMUL(py, P01, Rr[pc][0].xy); VPKFMA(px, P23, Rkk[c][0].zw, px); VPKFMA(py, P23, Rr[pc][0].zw, py);
;                         VPKFMA(px, P45, Rkk[c][1].xy, px); VPKFMA(py, P45, Rr[pc][1].xy, py); VPKFMA(px, P67, Rkk[c][1].zw, px); VPKFMA(py, P67, Rr[pc][1].zw, py);
;                         VADD(x, px.x, px.y); VADD(yp, py.x, py.y);
;                     } else {
;                         VPKMUL(px, P01, Rkk[c][0].xy); VPKFMA(px, P23, Rkk[c][0].zw, px); VPKFMA(px, P45, Rkk[c][1].xy, px); VPKFMA(px, P67, Rkk[c][1].zw, px);
;                         VADD(x, px.x, px.y);
;                     }
;                     asm volatile("" ::: "memory");
;                     if (s + 1 < 32) LOADREC((s + 1) & 1, s + 1);
;                     asm volatile("" ::: "memory");
;                     VPKMULBL(t01, vv2, Rkm[c][0].xy); VPKMULBL(t23, vv2, Rkm[c][0].zw);
;                     VDPP1(x); if (s >= 1) VDPP1(yp);
;                     VPKMULBL(t45, vv2, Rkm[c][1].xy); VPKMULBL(t67, vv2, Rkm[c][1].zw);
;                     VDPP2(x); if (s >= 1) VDPP2(yp);
;                     VPKFMA(P01, P01, Rw[c][0].xy, t01); VPKFMA(P23, P23, Rw[c][0].zw, t23);
;                     VDPP3(x); if (s >= 1) VDPP3(yp);
;                     VPKFMA(P45, P45, Rw[c][1].xy, t45); VPKFMA(P67, P67, Rw[c][1].zw, t67);
;                     if (s >= 1) { if (s - 1 < 8) YSHIFT(yk0); else if (s - 1 < 16) YSHIFT(yk1); else if (s - 1 < 24) YSHIFT(yk2); else YSHIFT(yk3); }
;                     x = x * si;
;                     f32x2 x2; x2.x = x; asm volatile("" : "+v"(x2));
;                     VPKNFMABL(P01, x2, Rka[c][0].xy, P01); VPKNFMABL(P23, x2, Rka[c][0].zw, P23); VPKNFMABL(P45, x2, Rka[c][1].xy, P45); VPKNFMABL(P67, x2, Rka[c][1].zw, P67);
;                 }
	ds_read_b128 v[80:83], v35 offset:4624
	ds_read_b128 v[84:87], v35 offset:4640
	ds_read_b128 v[104:107], v35 offset:30736
	ds_read_b128 v[108:111], v35 offset:30752
	ds_read_b32 v148, v36 offset:2176
	ds_read_b128 v[88:91], v35 offset:13328
	ds_read_b128 v[92:95], v35 offset:13344
	ds_read_b128 v[96:99], v35 offset:22032
	ds_read_b128 v[100:103], v35 offset:22048
	ds_read_b128 v[138:141], v35 offset:39440
	ds_read_b128 v[142:145], v35 offset:39456
	v_pk_mul_f32 v[8:9], v[4:5], v[48:49]
	v_pk_mul_f32 v[10:11], v[4:5], v[114:115]
	v_pk_fma_f32 v[8:9], v[6:7], v[50:51], v[8:9]
	v_pk_fma_f32 v[10:11], v[6:7], v[116:117], v[10:11]
	v_pk_fma_f32 v[8:9], v[0:1], v[52:53], v[8:9]
	v_pk_fma_f32 v[10:11], v[0:1], v[118:119], v[10:11]
	v_pk_fma_f32 v[8:9], v[2:3], v[54:55], v[8:9]
	v_pk_fma_f32 v[10:11], v[2:3], v[120:121], v[10:11]
	v_add_f32_e32 v12, v8, v9
	v_add_f32_e32 v14, v10, v11
	v_readlane_b32 s8, v34, 16
	v_pk_mul_f32 v[16:17], v[146:147], v[72:73] op_sel_hi:[0,1]
	v_pk_mul_f32 v[18:19], v[146:147], v[74:75] op_sel_hi:[0,1]
	v_add_f32_dpp v12, v12, v12 quad_perm:[1,0,3,2] row_mask:0xf bank_mask:0xf bound_ctrl:1
	v_add_f32_dpp v14, v14, v14 quad_perm:[1,0,3,2] row_mask:0xf bank_mask:0xf bound_ctrl:1
	v_pk_mul_f32 v[20:21], v[146:147], v[76:77] op_sel_hi:[0,1]
	v_pk_mul_f32 v[22:23], v[146:147], v[78:79] op_sel_hi:[0,1]
	v_add_f32_dpp v12, v12, v12 quad_perm:[2,3,0,1] row_mask:0xf bank_mask:0xf bound_ctrl:1
	v_add_f32_dpp v14, v14, v14 quad_perm:[2,3,0,1] row_mask:0xf bank_mask:0xf bound_ctrl:1
	v_pk_fma_f32 v[4:5], v[4:5], v[56:57], v[16:17]
	v_pk_fma_f32 v[6:7], v[6:7], v[58:59], v[18:19]
	v_add_f32_dpp v12, v12, v12 row_half_mirror row_mask:0xf bank_mask:0xf bound_ctrl:1
	v_add_f32_dpp v47, v14, v14 row_half_mirror row_mask:0xf bank_mask:0xa bound_ctrl:1
	v_pk_fma_f32 v[0:1], v[0:1], v[60:61], v[20:21]
	v_pk_fma_f32 v[2:3], v[2:3], v[62:63], v[22:23]
	v_mul_f32_e32 v12, s8, v12
	v_pk_fma_f32 v[4:5], v[12:13], v[64:65], v[4:5] op_sel_hi:[0,1,1] neg_lo:[1,0,0] neg_hi:[1,0,0]
	v_pk_fma_f32 v[6:7], v[12:13], v[66:67], v[6:7] op_sel_hi:[0,1,1] neg_lo:[1,0,0] neg_hi:[1,0,0]
	v_pk_fma_f32 v[0:1], v[12:13], v[68:69], v[0:1] op_sel_hi:[0,1,1] neg_lo:[1,0,0] neg_hi:[1,0,0]
	v_pk_fma_f32 v[2:3], v[12:13], v[70:71], v[2:3] op_sel_hi:[0,1,1] neg_lo:[1,0,0] neg_hi:[1,0,0]
	s_waitcnt lgkmcnt(0)
	ds_read_b128 v[48:51], v35 offset:4896
	ds_read_b128 v[52:55], v35 offset:4912
	ds_read_b128 v[72:75], v35 offset:31008
	ds_read_b128 v[76:79], v35 offset:31024
	ds_read_b32 v146, v36 offset:2304
	ds_read_b128 v[56:59], v35 offset:13600
	ds_read_b128 v[60:63], v35 offset:13616
	ds_read_b128 v[64:67], v35 offset:22304
	ds_read_b128 v[68:71], v35 offset:22320
	ds_read_b128 v[114:117], v35 offset:39712
	ds_read_b128 v[118:121], v35 offset:39728
	v_pk_mul_f32 v[8:9], v[4:5], v[80:81]
	v_pk_mul_f32 v[10:11], v[4:5], v[122:123]
	v_pk_fma_f32 v[8:9], v[6:7], v[82:83], v[8:9]
	v_pk_fma_f32 v[10:11], v[6:7], v[124:125], v[10:11]
	v_pk_fma_f32 v[8:9], v[0:1], v[84:85], v[8:9]
	v_pk_fma_f32 v[10:11], v[0:1], v[126:127], v[10:11]
	v_pk_fma_f32 v[8:9], v[2:3], v[86:87], v[8:9]
	v_pk_fma_f32 v[10:11], v[2:3], v[128:129], v[10:11]
	v_add_f32_e32 v12, v8, v9
	v_add_f32_e32 v14, v10, v11
	v_readlane_b32 s8, v34, 17
	v_pk_mul_f32 v[16:17], v[148:149], v[104:105] op_sel_hi:[0,1]
	v_pk_mul_f32 v[18:19], v[148:149], v[106:107] op_sel_hi:[0,1]
	v_add_f32_dpp v12, v12, v12 quad_perm:[1,0,3,2] row_mask:0xf bank_mask:0xf bound_ctrl:1
	v_add_f32_dpp v14, v14, v14 quad_perm:[1,0,3,2] row_mask:0xf bank_mask:0xf bound_ctrl:1
	v_pk_mul_f32 v[20:21], v[148:149], v[108:109] op_sel_hi:[0,1]
	v_pk_mul_f32 v[22:23], v[148:149], v[110:111] op_sel_hi:[0,1]
	v_add_f32_dpp v12, v12, v12 quad_perm:[2,3,0,1] row_mask:0xf bank_mask:0xf bound_ctrl:1
	v_add_f32_dpp v14, v14, v14 quad_perm:[2,3,0,1] row_mask:0xf bank_mask:0xf bound_ctrl:1
	v_pk_fma_f32 v[4:5], v[4:5], v[88:89], v[16:17]
	v_pk_fma_f32 v[6:7], v[6:7], v[90:91], v[18:19]
	v_add_f32_dpp v12, v12, v12 row_half_mirror row_mask:0xf bank_mask:0xf bound_ctrl:1
	v_add_f32_dpp v150, v14, v14 row_half_mirror row_mask:0xf bank_mask:0x5 bound_ctrl:1
	v_pk_fma_f32 v[0:1], v[0:1], v[92:93], v[20:21]
	v_pk_fma_f32 v[2:3], v[2:3], v[94:95], v[22:23]
	v_mul_f32_e32 v12, s8, v12
	v_pk_fma_f32 v[4:5], v[12:13], v[96:97], v[4:5] op_sel_hi:[0,1,1] neg_lo:[1,0,0] neg_hi:[1,0,0]
	v_pk_fma_f32 v[6:7], v[12:13], v[98:99], v[6:7] op_sel_hi:[0,1,1] neg_lo:[1,0,0] neg_hi:[1,0,0]
	v_pk_fma_f32 v[0:1], v[12:13], v[100:101], v[0:1] op_sel_hi:[0,1,1] neg_lo:[1,0,0] neg_hi:[1,0,0]
	v_pk_fma_f32 v[2:3], v[12:13], v[102:103], v[2:3] op_sel_hi:[0,1,1] neg_lo:[1,0,0] neg_hi:[1,0,0]
	s_waitcnt lgkmcnt(0)
; __device__ __forceinline__ void scan_half(const Params& p, LAS unsigned char* lds, int pi, int rh, int pass) {
;     ...
;                 for (int s = 0; s < 32; ++s) {
;                     const int c = s & 1, pc = c ^ 1;
;                     const float si = __int_as_float(__builtin_amdgcn_readlane(__float_as_int(inv2), s));
;                     f32x2 px, py, t01, t23, t45, t67; float x;
;                     f32x2 vv2; vv2.x = Rv[c]; asm volatile("" : "+v"(vv2));
;                     if (s >= 1) {
;                         VPKMUL(px, P01, Rkk[c][0].xy); VPKMUL(py, P01, Rr[pc][0].xy); VPKFMA(px, P23, Rkk[c][0].zw, px); VPKFMA(py, P23, Rr[pc][0].zw, py);
;                         VPKFMA(px, P45, Rkk[c][1].xy, px); VPKFMA(py, P45, Rr[pc][1].xy, py); VPKFMA(px, P67, Rkk[c][1].zw, px); VPKFMA(py, P67, Rr[pc][1].zw, py);
;                         VADD(x, px.x, px.y); VADD(yp, py.x, py.y);
;                     } else {
;                         VPKMUL(px, P01, Rkk[c][0].xy); VPKFMA(px, P23, Rkk[c][0].zw, px); VPKFMA(px, P45, Rkk[c][1].xy, px); VPKFMA(px, P67, Rkk[c][1].zw, px);
;                         VADD(x, px.x, px.y);
;                     }
;                     asm volatile("" ::: "memory");
;                     if (s + 1 < 32) LOADREC((s + 1) & 1, s + 1);
;                     asm volatile("" ::: "memory");
;                     VPKMULBL(t01, vv2, Rkm[c][0].xy); VPKMULBL(t23, vv2, Rkm[c][0].zw);
;                     VDPP1(x); if (s >= 1) VDPP1(yp);
;                     VPKMULBL(t45, vv2, Rkm[c][1].xy); VPKMULBL(t67, vv2, Rkm[c][1].zw);
;                     VDPP2(x); if (s >= 1) VDPP2(yp);
;                     VPKFMA(P01, P01, Rw[c][0].xy, t01); VPKFMA(P23, P23, Rw[c][0].zw, t23);
;                     VDPP3(x); if (s >= 1) VDPP3(yp);
;                     VPKFMA(P45, P45, Rw[c][1].xy, t45); VPKFMA(P67, P67, Rw[c][1].zw, t67);
;                     if (s >= 1) { if (s - 1 < 8) YSHIFT(yk0); else if (s - 1 < 16) YSHIFT(yk1); else if (s - 1 < 24) YSHIFT(yk2); else YSHIFT(yk3); }
;                     x = x * si;
;                     f32x2 x2; x2.x = x; asm volatile("" : "+v"(x2));
;                     VPKNFMABL(P01, x2, Rka[c][0].xy, P01); VPKNFMABL(P23, x2, Rka[c][0].zw, P23); VPKNFMABL(P45, x2, Rka[c][1].xy, P45); VPKNFMABL(P67, x2, Rka[c][1].zw, P67);
;                 }
	ds_read_b128 v[80:83], v35 offset:5168
	ds_read_b128 v[84:87], v35 offset:5184
	ds_read_b128 v[104:107], v35 offset:31280
	ds_read_b128 v[108:111], v35 offset:31296
	ds_read_b32 v148, v36 offset:2432
	ds_read_b128 v[88:91], v35 offset:13872
	ds_read_b128 v[92:95], v35 offset:13888
	ds_read_b128 v[96:99], v35 offset:22576
	ds_read_b128 v[100:103], v35 offset:22592
	ds_read_b128 v[122:125], v35 offset:39984
	ds_read_b128 v[126:129], v35 offset:40000
	v_pk_mul_f32 v[8:9], v[4:5], v[48:49]
	v_pk_mul_f32 v[10:11], v[4:5], v[138:139]
	v_pk_fma_f32 v[8:9], v[6:7], v[50:51], v[8:9]
	v_pk_fma_f32 v[10:11], v[6:7], v[140:141], v[10:11]
	v_pk_fma_f32 v[8:9], v[0:1], v[52:53], v[8:9]
	v_pk_fma_f32 v[10:11], v[0:1], v[142:143], v[10:11]
	v_pk_fma_f32 v[8:9], v[2:3], v[54:55], v[8:9]
	v_pk_fma_f32 v[10:11], v[2:3], v[144:145], v[10:11]
	v_add_f32_e32 v12, v8, v9
	v_add_f32_e32 v14, v10, v11
	v_readlane_b32 s8, v34, 18
	v_pk_mul_f32 v[16:17], v[146:147], v[72:73] op_sel_hi:[0,1]
	v_pk_mul_f32 v[18:19], v[146:147], v[74:75] op_sel_hi:[0,1]
	v_add_f32_dpp v12, v12, v12 quad_perm:[1,0,3,2] row_mask:0xf bank_mask:0xf bound_ctrl:1
	v_add_f32_dpp v14, v14, v14 quad_perm:[1,0,3,2] row_mask:0xf bank_mask:0xf bound_ctrl:1
	v_pk_mul_f32 v[20:21], v[146:147], v[76:77] op_sel_hi:[0,1]
	v_pk_mul_f32 v[22:23], v[146:147], v[78:79] op_sel_hi:[0,1]
	v_add_f32_dpp v12, v12, v12 quad_perm:[2,3,0,1] row_mask:0xf bank_mask:0xf bound_ctrl:1
	v_add_f32_dpp v14, v14, v14 quad_perm:[2,3,0,1] row_mask:0xf bank_mask:0xf bound_ctrl:1
	v_pk_fma_f32 v[4:5], v[4:5], v[56:57], v[16:17]
	v_pk_fma_f32 v[6:7], v[6:7], v[58:59], v[18:19]
	v_add_f32_dpp v12, v12, v12 row_half_mirror row_mask:0xf bank_mask:0xf bound_ctrl:1
	v_add_f32_dpp v150, v14, v14 row_half_mirror row_mask:0xf bank_mask:0xa bound_ctrl:1
	v_pk_fma_f32 v[0:1], v[0:1], v[60:61], v[20:21]
	v_pk_fma_f32 v[2:3], v[2:3], v[62:63], v[22:23]
	v_mul_f32_e32 v12, s8, v12
	v_pk_fma_f32 v[4:5], v[12:13], v[64:65], v[4:5] op_sel_hi:[0,1,1] neg_lo:[1,0,0] neg_hi:[1,0,0]
	v_pk_fma_f32 v[6:7], v[12:13], v[66:67], v[6:7] op_sel_hi:[0,1,1] neg_lo:[1,0,0] neg_hi:[1,0,0]
	v_pk_fma_f32 v[0:1], v[12:13], v[68:69], v[0:1] op_sel_hi:[0,1,1] neg_lo:[1,0,0] neg_hi:[1,0,0]
	v_pk_fma_f32 v[2:3], v[12:13], v[70:71], v[2:3] op_sel_hi:[0,1,1] neg_lo:[1,0,0] neg_hi:[1,0,0]
	s_waitcnt lgkmcnt(0)
	ds_read_b128 v[48:51], v35 offset:5440
	ds_read_b128 v[52:55], v35 offset:5456
	ds_read_b128 v[72:75], v35 offset:31552
	ds_read_b128 v[76:79], v35 offset:31568
	ds_read_b32 v146, v36 offset:2560
	ds_read_b128 v[56:59], v35 offset:14144
	ds_read_b128 v[60:63], v35 offset:14160
	ds_read_b128 v[64:67], v35 offset:22848
	ds_read_b128 v[68:71], v35 offset:22864
	ds_read_b128 v[138:141], v35 offset:40256
	ds_read_b128 v[142:145], v35 offset:40272
	v_pk_mul_f32 v[8:9], v[4:5], v[80:81]
	v_pk_mul_f32 v[10:11], v[4:5], v[114:115]
	v_pk_fma_f32 v[8:9], v[6:7], v[82:83], v[8:9]
	v_pk_fma_f32 v[10:11], v[6:7], v[116:117], v[10:11]
	v_pk_fma_f32 v[8:9], v[0:1], v[84:85], v[8:9]
	v_pk_fma_f32 v[10:11], v[0:1], v[118:119], v[10:11]
	v_pk_fma_f32 v[8:9], v[2:3], v[86:87], v[8:9]
	v_pk_fma_f32 v[10:11], v[2:3], v[120:121], v[10:11]
	v_add_f32_e32 v12, v8, v9
	v_add_f32_e32 v14, v10, v11
	v_readlane_b32 s8, v34, 19
	v_pk_mul_f32 v[16:17], v[148:149], v[104:105] op_sel_hi:[0,1]
	v_pk_mul_f32 v[18:19], v[148:149], v[106:107] op_sel_hi:[0,1]
	v_add_f32_dpp v12, v12, v12 quad_perm:[1,0,3,2] row_mask:0xf bank_mask:0xf bound_ctrl:1
	v_add_f32_dpp v14, v14, v14 quad_perm:[1,0,3,2] row_mask:0xf bank_mask:0xf bound_ctrl:1
	v_pk_mul_f32 v[20:21], v[148:149], v[108:109] op_sel_hi:[0,1]
	v_pk_mul_f32 v[22:23], v[148:149], v[110:111] op_sel_hi:[0,1]
	v_add_f32_dpp v12, v12, v12 quad_perm:[2,3,0,1] row_mask:0xf bank_mask:0xf bound_ctrl:1
	v_add_f32_dpp v14, v14, v14 quad_perm:[2,3,0,1] row_mask:0xf bank_mask:0xf bound_ctrl:1
	v_pk_fma_f32 v[4:5], v[4:5], v[88:89], v[16:17]
	v_pk_fma_f32 v[6:7], v[6:7], v[90:91], v[18:19]
	v_add_f32_dpp v12, v12, v12 row_half_mirror row_mask:0xf bank_mask:0xf bound_ctrl:1
	v_add_f32_dpp v151, v14, v14 row_half_mirror row_mask:0xf bank_mask:0x5 bound_ctrl:1
	v_pk_fma_f32 v[0:1], v[0:1], v[92:93], v[20:21]
	v_pk_fma_f32 v[2:3], v[2:3], v[94:95], v[22:23]
	v_mul_f32_e32 v12, s8, v12
	v_pk_fma_f32 v[4:5], v[12:13], v[96:97], v[4:5] op_sel_hi:[0,1,1] neg_lo:[1,0,0] neg_hi:[1,0,0]
	v_pk_fma_f32 v[6:7], v[12:13], v[98:99], v[6:7] op_sel_hi:[0,1,1] neg_lo:[1,0,0] neg_hi:[1,0,0]
	v_pk_fma_f32 v[0:1], v[12:13], v[100:101], v[0:1] op_sel_hi:[0,1,1] neg_lo:[1,0,0] neg_hi:[1,0,0]
	v_pk_fma_f32 v[2:3], v[12:13], v[102:103], v[2:3] op_sel_hi:[0,1,1] neg_lo:[1,0,0] neg_hi:[1,0,0]
	s_waitcnt lgkmcnt(0)
; __device__ __forceinline__ void scan_half(const Params& p, LAS unsigned char* lds, int pi, int rh, int pass) {
;     ...
;                 for (int s = 0; s < 32; ++s) {
;                     const int c = s & 1, pc = c ^ 1;
;                     const float si = __int_as_float(__builtin_amdgcn_readlane(__float_as_int(inv2), s));
;                     f32x2 px, py, t01, t23, t45, t67; float x;
;                     f32x2 vv2; vv2.x = Rv[c]; asm volatile("" : "+v"(vv2));
;                     if (s >= 1) {
;                         VPKMUL(px, P01, Rkk[c][0].xy); VPKMUL(py, P01, Rr[pc][0].xy); VPKFMA(px, P23, Rkk[c][0].zw, px); VPKFMA(py, P23, Rr[pc][0].zw, py);
;                         VPKFMA(px, P45, Rkk[c][1].xy, px); VPKFMA(py, P45, Rr[pc][1].xy, py); VPKFMA(px, P67, Rkk[c][1].zw, px); VPKFMA(py, P67, Rr[pc][1].zw, py);
;                         VADD(x, px.x, px.y); VADD(yp, py.x, py.y);
;                     } else {
;                         VPKMUL(px, P01, Rkk[c][0].xy); VPKFMA(px, P23, Rkk[c][0].zw, px); VPKFMA(px, P45, Rkk[c][1].xy, px); VPKFMA(px, P67, Rkk[c][1].zw, px);
;                         VADD(x, px.x, px.y);
;                     }
;                     asm volatile("" ::: "memory");
;                     if (s + 1 < 32) LOADREC((s + 1) & 1, s + 1);
;                     asm volatile("" ::: "memory");
;                     VPKMULBL(t01, vv2, Rkm[c][0].xy); VPKMULBL(t23, vv2, Rkm[c][0].zw);
;                     VDPP1(x); if (s >= 1) VDPP1(yp);
;                     VPKMULBL(t45, vv2, Rkm[c][1].xy); VPKMULBL(t67, vv2, Rkm[c][1].zw);
;                     VDPP2(x); if (s >= 1) VDPP2(yp);
;                     VPKFMA(P01, P01, Rw[c][0].xy, t01); VPKFMA(P23, P23, Rw[c][0].zw, t23);
;                     VDPP3(x); if (s >= 1) VDPP3(yp);
;                     VPKFMA(P45, P45, Rw[c][1].xy, t45); VPKFMA(P67, P67, Rw[c][1].zw, t67);
;                     if (s >= 1) { if (s - 1 < 8) YSHIFT(yk0); else if (s - 1 < 16) YSHIFT(yk1); else if (s - 1 < 24) YSHIFT(yk2); else YSHIFT(yk3); }
;                     x = x * si;
;                     f32x2 x2; x2.x = x; asm volatile("" : "+v"(x2));
;                     VPKNFMABL(P01, x2, Rka[c][0].xy, P01); VPKNFMABL(P23, x2, Rka[c][0].zw, P23); VPKNFMABL(P45, x2, Rka[c][1].xy, P45); VPKNFMABL(P67, x2, Rka[c][1].zw, P67);
;                 }
	ds_read_b128 v[80:83], v35 offset:5712
	ds_read_b128 v[84:87], v35 offset:5728
	ds_read_b128 v[104:107], v35 offset:31824
	ds_read_b128 v[108:111], v35 offset:31840
	ds_read_b32 v148, v36 offset:2688
	ds_read_b128 v[88:91], v35 offset:14416
	ds_read_b128 v[92:95], v35 offset:14432
	ds_read_b128 v[96:99], v35 offset:23120
	ds_read_b128 v[100:103], v35 offset:23136
	ds_read_b128 v[114:117], v35 offset:40528
	ds_read_b128 v[118:121], v35 offset:40544
	v_pk_mul_f32 v[8:9], v[4:5], v[48:49]
	v_pk_mul_f32 v[10:11], v[4:5], v[122:123]
	v_pk_fma_f32 v[8:9], v[6:7], v[50:51], v[8:9]
	v_pk_fma_f32 v[10:11], v[6:7], v[124:125], v[10:11]
	v_pk_fma_f32 v[8:9], v[0:1], v[52:53], v[8:9]
	v_pk_fma_f32 v[10:11], v[0:1], v[126:127], v[10:11]
	v_pk_fma_f32 v[8:9], v[2:3], v[54:55], v[8:9]
	v_pk_fma_f32 v[10:11], v[2:3], v[128:129], v[10:11]
	v_add_f32_e32 v12, v8, v9
	v_add_f32_e32 v14, v10, v11
	v_readlane_b32 s8, v34, 20
	v_pk_mul_f32 v[16:17], v[146:147], v[72:73] op_sel_hi:[0,1]
	v_pk_mul_f32 v[18:19], v[146:147], v[74:75] op_sel_hi:[0,1]
	v_add_f32_dpp v12, v12, v12 quad_perm:[1,0,3,2] row_mask:0xf bank_mask:0xf bound_ctrl:1
	v_add_f32_dpp v14, v14, v14 quad_perm:[1,0,3,2] row_mask:0xf bank_mask:0xf bound_ctrl:1
	v_pk_mul_f32 v[20:21], v[146:147], v[76:77] op_sel_hi:[0,1]
	v_pk_mul_f32 v[22:23], v[146:147], v[78:79] op_sel_hi:[0,1]
	v_add_f32_dpp v12, v12, v12 quad_perm:[2,3,0,1] row_mask:0xf bank_mask:0xf bound_ctrl:1
	v_add_f32_dpp v14, v14, v14 quad_perm:[2,3,0,1] row_mask:0xf bank_mask:0xf bound_ctrl:1
	v_pk_fma_f32 v[4:5], v[4:5], v[56:57], v[16:17]
	v_pk_fma_f32 v[6:7], v[6:7], v[58:59], v[18:19]
	v_add_f32_dpp v12, v12, v12 row_half_mirror row_mask:0xf bank_mask:0xf bound_ctrl:1
	v_add_f32_dpp v151, v14, v14 row_half_mirror row_mask:0xf bank_mask:0xa bound_ctrl:1
	v_pk_fma_f32 v[0:1], v[0:1], v[60:61], v[20:21]
	v_pk_fma_f32 v[2:3], v[2:3], v[62:63], v[22:23]
	v_mul_f32_e32 v12, s8, v12
	v_pk_fma_f32 v[4:5], v[12:13], v[64:65], v[4:5] op_sel_hi:[0,1,1] neg_lo:[1,0,0] neg_hi:[1,0,0]
	v_pk_fma_f32 v[6:7], v[12:13], v[66:67], v[6:7] op_sel_hi:[0,1,1] neg_lo:[1,0,0] neg_hi:[1,0,0]
	v_pk_fma_f32 v[0:1], v[12:13], v[68:69], v[0:1] op_sel_hi:[0,1,1] neg_lo:[1,0,0] neg_hi:[1,0,0]
	v_pk_fma_f32 v[2:3], v[12:13], v[70:71], v[2:3] op_sel_hi:[0,1,1] neg_lo:[1,0,0] neg_hi:[1,0,0]
	s_waitcnt lgkmcnt(0)
	ds_read_b128 v[48:51], v35 offset:5984
	ds_read_b128 v[52:55], v35 offset:6000
	ds_read_b128 v[72:75], v35 offset:32096
	ds_read_b128 v[76:79], v35 offset:32112
	ds_read_b32 v146, v36 offset:2816
	ds_read_b128 v[56:59], v35 offset:14688
	ds_read_b128 v[60:63], v35 offset:14704
	ds_read_b128 v[64:67], v35 offset:23392
	ds_read_b128 v[68:71], v35 offset:23408
	ds_read_b128 v[122:125], v35 offset:40800
	ds_read_b128 v[126:129], v35 offset:40816
	v_pk_mul_f32 v[8:9], v[4:5], v[80:81]
	v_pk_mul_f32 v[10:11], v[4:5], v[138:139]
	v_pk_fma_f32 v[8:9], v[6:7], v[82:83], v[8:9]
	v_pk_fma_f32 v[10:11], v[6:7], v[140:141], v[10:11]
	v_pk_fma_f32 v[8:9], v[0:1], v[84:85], v[8:9]
	v_pk_fma_f32 v[10:11], v[0:1], v[142:143], v[10:11]
	v_pk_fma_f32 v[8:9], v[2:3], v[86:87], v[8:9]
	v_pk_fma_f32 v[10:11], v[2:3], v[144:145], v[10:11]
	v_add_f32_e32 v12, v8, v9
	v_add_f32_e32 v14, v10, v11
	v_readlane_b32 s8, v34, 21
	v_pk_mul_f32 v[16:17], v[148:149], v[104:105] op_sel_hi:[0,1]
	v_pk_mul_f32 v[18:19], v[148:149], v[106:107] op_sel_hi:[0,1]
	v_add_f32_dpp v12, v12, v12 quad_perm:[1,0,3,2] row_mask:0xf bank_mask:0xf bound_ctrl:1
	v_add_f32_dpp v14, v14, v14 quad_perm:[1,0,3,2] row_mask:0xf bank_mask:0xf bound_ctrl:1
	v_pk_mul_f32 v[20:21], v[148:149], v[108:109] op_sel_hi:[0,1]
	v_pk_mul_f32 v[22:23], v[148:149], v[110:111] op_sel_hi:[0,1]
	v_add_f32_dpp v12, v12, v12 quad_perm:[2,3,0,1] row_mask:0xf bank_mask:0xf bound_ctrl:1
	v_add_f32_dpp v14, v14, v14 quad_perm:[2,3,0,1] row_mask:0xf bank_mask:0xf bound_ctrl:1
	v_pk_fma_f32 v[4:5], v[4:5], v[88:89], v[16:17]
	v_pk_fma_f32 v[6:7], v[6:7], v[90:91], v[18:19]
	v_add_f32_dpp v12, v12, v12 row_half_mirror row_mask:0xf bank_mask:0xf bound_ctrl:1
	v_add_f32_dpp v152, v14, v14 row_half_mirror row_mask:0xf bank_mask:0x5 bound_ctrl:1
	v_pk_fma_f32 v[0:1], v[0:1], v[92:93], v[20:21]
	v_pk_fma_f32 v[2:3], v[2:3], v[94:95], v[22:23]
	v_mul_f32_e32 v12, s8, v12
	v_pk_fma_f32 v[4:5], v[12:13], v[96:97], v[4:5] op_sel_hi:[0,1,1] neg_lo:[1,0,0] neg_hi:[1,0,0]
	v_pk_fma_f32 v[6:7], v[12:13], v[98:99], v[6:7] op_sel_hi:[0,1,1] neg_lo:[1,0,0] neg_hi:[1,0,0]
	v_pk_fma_f32 v[0:1], v[12:13], v[100:101], v[0:1] op_sel_hi:[0,1,1] neg_lo:[1,0,0] neg_hi:[1,0,0]
	v_pk_fma_f32 v[2:3], v[12:13], v[102:103], v[2:3] op_sel_hi:[0,1,1] neg_lo:[1,0,0] neg_hi:[1,0,0]
	s_waitcnt lgkmcnt(0)
; __device__ __forceinline__ void scan_half(const Params& p, LAS unsigned char* lds, int pi, int rh, int pass) {
;     ...
;                 for (int s = 0; s < 32; ++s) {
;                     const int c = s & 1, pc = c ^ 1;
;                     const float si = __int_as_float(__builtin_amdgcn_readlane(__float_as_int(inv2), s));
;                     f32x2 px, py, t01, t23, t45, t67; float x;
;                     f32x2 vv2; vv2.x = Rv[c]; asm volatile("" : "+v"(vv2));
;                     if (s >= 1) {
;                         VPKMUL(px, P01, Rkk[c][0].xy); VPKMUL(py, P01, Rr[pc][0].xy); VPKFMA(px, P23, Rkk[c][0].zw, px); VPKFMA(py, P23, Rr[pc][0].zw, py);
;                         VPKFMA(px, P45, Rkk[c][1].xy, px); VPKFMA(py, P45, Rr[pc][1].xy, py); VPKFMA(px, P67, Rkk[c][1].zw, px); VPKFMA(py, P67, Rr[pc][1].zw, py);
;                         VADD(x, px.x, px.y); VADD(yp, py.x, py.y);
;                     } else {
;                         VPKMUL(px, P01, Rkk[c][0].xy); VPKFMA(px, P23, Rkk[c][0].zw, px); VPKFMA(px, P45, Rkk[c][1].xy, px); VPKFMA(px, P67, Rkk[c][1].zw, px);
;                         VADD(x, px.x, px.y);
;                     }
;                     asm volatile("" ::: "memory");
;                     if (s + 1 < 32) LOADREC((s + 1) & 1, s + 1);
;                     asm volatile("" ::: "memory");
;                     VPKMULBL(t01, vv2, Rkm[c][0].xy); VPKMULBL(t23, vv2, Rkm[c][0].zw);
;                     VDPP1(x); if (s >= 1) VDPP1(yp);
;                     VPKMULBL(t45, vv2, Rkm[c][1].xy); VPKMULBL(t67, vv2, Rkm[c][1].zw);
;                     VDPP2(x); if (s >= 1) VDPP2(yp);
;                     VPKFMA(P01, P01, Rw[c][0].xy, t01); VPKFMA(P23, P23, Rw[c][0].zw, t23);
;                     VDPP3(x); if (s >= 1) VDPP3(yp);
;                     VPKFMA(P45, P45, Rw[c][1].xy, t45); VPKFMA(P67, P67, Rw[c][1].zw, t67);
;                     if (s >= 1) { if (s - 1 < 8) YSHIFT(yk0); else if (s - 1 < 16) YSHIFT(yk1); else if (s - 1 < 24) YSHIFT(yk2); else YSHIFT(yk3); }
;                     x = x * si;
;                     f32x2 x2; x2.x = x; asm volatile("" : "+v"(x2));
;                     VPKNFMABL(P01, x2, Rka[c][0].xy, P01); VPKNFMABL(P23, x2, Rka[c][0].zw, P23); VPKNFMABL(P45, x2, Rka[c][1].xy, P45); VPKNFMABL(P67, x2, Rka[c][1].zw, P67);
;                 }
	ds_read_b128 v[80:83], v35 offset:6256
	ds_read_b128 v[84:87], v35 offset:6272
	ds_read_b128 v[104:107], v35 offset:32368
	ds_read_b128 v[108:111], v35 offset:32384
	ds_read_b32 v148, v36 offset:2944
	ds_read_b128 v[88:91], v35 offset:14960
	ds_read_b128 v[92:95], v35 offset:14976
	ds_read_b128 v[96:99], v35 offset:23664
	ds_read_b128 v[100:103], v35 offset:23680
	ds_read_b128 v[138:141], v35 offset:41072
	ds_read_b128 v[142:145], v35 offset:41088
	v_pk_mul_f32 v[8:9], v[4:5], v[48:49]
	v_pk_mul_f32 v[10:11], v[4:5], v[114:115]
	v_pk_fma_f32 v[8:9], v[6:7], v[50:51], v[8:9]
	v_pk_fma_f32 v[10:11], v[6:7], v[116:117], v[10:11]
	v_pk_fma_f32 v[8:9], v[0:1], v[52:53], v[8:9]
	v_pk_fma_f32 v[10:11], v[0:1], v[118:119], v[10:11]
	v_pk_fma_f32 v[8:9], v[2:3], v[54:55], v[8:9]
	v_pk_fma_f32 v[10:11], v[2:3], v[120:121], v[10:11]
	v_add_f32_e32 v12, v8, v9
	v_add_f32_e32 v14, v10, v11
	v_readlane_b32 s8, v34, 22
	v_pk_mul_f32 v[16:17], v[146:147], v[72:73] op_sel_hi:[0,1]
	v_pk_mul_f32 v[18:19], v[146:147], v[74:75] op_sel_hi:[0,1]
	v_add_f32_dpp v12, v12, v12 quad_perm:[1,0,3,2] row_mask:0xf bank_mask:0xf bound_ctrl:1
	v_add_f32_dpp v14, v14, v14 quad_perm:[1,0,3,2] row_mask:0xf bank_mask:0xf bound_ctrl:1
	v_pk_mul_f32 v[20:21], v[146:147], v[76:77] op_sel_hi:[0,1]
	v_pk_mul_f32 v[22:23], v[146:147], v[78:79] op_sel_hi:[0,1]
	v_add_f32_dpp v12, v12, v12 quad_perm:[2,3,0,1] row_mask:0xf bank_mask:0xf bound_ctrl:1
	v_add_f32_dpp v14, v14, v14 quad_perm:[2,3,0,1] row_mask:0xf bank_mask:0xf bound_ctrl:1
	v_pk_fma_f32 v[4:5], v[4:5], v[56:57], v[16:17]
	v_pk_fma_f32 v[6:7], v[6:7], v[58:59], v[18:19]
	v_add_f32_dpp v12, v12, v12 row_half_mirror row_mask:0xf bank_mask:0xf bound_ctrl:1
	v_add_f32_dpp v152, v14, v14 row_half_mirror row_mask:0xf bank_mask:0xa bound_ctrl:1
	v_pk_fma_f32 v[0:1], v[0:1], v[60:61], v[20:21]
	v_pk_fma_f32 v[2:3], v[2:3], v[62:63], v[22:23]
	v_mul_f32_e32 v12, s8, v12
	v_pk_fma_f32 v[4:5], v[12:13], v[64:65], v[4:5] op_sel_hi:[0,1,1] neg_lo:[1,0,0] neg_hi:[1,0,0]
	v_pk_fma_f32 v[6:7], v[12:13], v[66:67], v[6:7] op_sel_hi:[0,1,1] neg_lo:[1,0,0] neg_hi:[1,0,0]
	v_pk_fma_f32 v[0:1], v[12:13], v[68:69], v[0:1] op_sel_hi:[0,1,1] neg_lo:[1,0,0] neg_hi:[1,0,0]
	v_pk_fma_f32 v[2:3], v[12:13], v[70:71], v[2:3] op_sel_hi:[0,1,1] neg_lo:[1,0,0] neg_hi:[1,0,0]
	s_waitcnt lgkmcnt(0)
	ds_read_b128 v[48:51], v35 offset:6528
	ds_read_b128 v[52:55], v35 offset:6544
	ds_read_b128 v[72:75], v35 offset:32640
	ds_read_b128 v[76:79], v35 offset:32656
	ds_read_b32 v146, v36 offset:3072
	ds_read_b128 v[56:59], v35 offset:15232
	ds_read_b128 v[60:63], v35 offset:15248
	ds_read_b128 v[64:67], v35 offset:23936
	ds_read_b128 v[68:71], v35 offset:23952
	ds_read_b128 v[114:117], v35 offset:41344
	ds_read_b128 v[118:121], v35 offset:41360
	v_pk_mul_f32 v[8:9], v[4:5], v[80:81]
	v_pk_mul_f32 v[10:11], v[4:5], v[122:123]
	v_pk_fma_f32 v[8:9], v[6:7], v[82:83], v[8:9]
	v_pk_fma_f32 v[10:11], v[6:7], v[124:125], v[10:11]
	v_pk_fma_f32 v[8:9], v[0:1], v[84:85], v[8:9]
	v_pk_fma_f32 v[10:11], v[0:1], v[126:127], v[10:11]
	v_pk_fma_f32 v[8:9], v[2:3], v[86:87], v[8:9]
	v_pk_fma_f32 v[10:11], v[2:3], v[128:129], v[10:11]
	v_add_f32_e32 v12, v8, v9
	v_add_f32_e32 v14, v10, v11
	v_readlane_b32 s8, v34, 23
	v_pk_mul_f32 v[16:17], v[148:149], v[104:105] op_sel_hi:[0,1]
	v_pk_mul_f32 v[18:19], v[148:149], v[106:107] op_sel_hi:[0,1]
	v_add_f32_dpp v12, v12, v12 quad_perm:[1,0,3,2] row_mask:0xf bank_mask:0xf bound_ctrl:1
	v_add_f32_dpp v14, v14, v14 quad_perm:[1,0,3,2] row_mask:0xf bank_mask:0xf bound_ctrl:1
	v_pk_mul_f32 v[20:21], v[148:149], v[108:109] op_sel_hi:[0,1]
	v_pk_mul_f32 v[22:23], v[148:149], v[110:111] op_sel_hi:[0,1]
	v_add_f32_dpp v12, v12, v12 quad_perm:[2,3,0,1] row_mask:0xf bank_mask:0xf bound_ctrl:1
	v_add_f32_dpp v14, v14, v14 quad_perm:[2,3,0,1] row_mask:0xf bank_mask:0xf bound_ctrl:1
	v_pk_fma_f32 v[4:5], v[4:5], v[88:89], v[16:17]
	v_pk_fma_f32 v[6:7], v[6:7], v[90:91], v[18:19]
	v_add_f32_dpp v12, v12, v12 row_half_mirror row_mask:0xf bank_mask:0xf bound_ctrl:1
	v_add_f32_dpp v153, v14, v14 row_half_mirror row_mask:0xf bank_mask:0x5 bound_ctrl:1
	v_pk_fma_f32 v[0:1], v[0:1], v[92:93], v[20:21]
	v_pk_fma_f32 v[2:3], v[2:3], v[94:95], v[22:23]
	v_mul_f32_e32 v12, s8, v12
	v_pk_fma_f32 v[4:5], v[12:13], v[96:97], v[4:5] op_sel_hi:[0,1,1] neg_lo:[1,0,0] neg_hi:[1,0,0]
	v_pk_fma_f32 v[6:7], v[12:13], v[98:99], v[6:7] op_sel_hi:[0,1,1] neg_lo:[1,0,0] neg_hi:[1,0,0]
	v_pk_fma_f32 v[0:1], v[12:13], v[100:101], v[0:1] op_sel_hi:[0,1,1] neg_lo:[1,0,0] neg_hi:[1,0,0]
	v_pk_fma_f32 v[2:3], v[12:13], v[102:103], v[2:3] op_sel_hi:[0,1,1] neg_lo:[1,0,0] neg_hi:[1,0,0]
	s_waitcnt lgkmcnt(0)
; __device__ __forceinline__ void scan_half(const Params& p, LAS unsigned char* lds, int pi, int rh, int pass) {
;     ...
;                 for (int s = 0; s < 32; ++s) {
;                     const int c = s & 1, pc = c ^ 1;
;                     const float si = __int_as_float(__builtin_amdgcn_readlane(__float_as_int(inv2), s));
;                     f32x2 px, py, t01, t23, t45, t67; float x;
;                     f32x2 vv2; vv2.x = Rv[c]; asm volatile("" : "+v"(vv2));
;                     if (s >= 1) {
;                         VPKMUL(px, P01, Rkk[c][0].xy); VPKMUL(py, P01, Rr[pc][0].xy); VPKFMA(px, P23, Rkk[c][0].zw, px); VPKFMA(py, P23, Rr[pc][0].zw, py);
;                         VPKFMA(px, P45, Rkk[c][1].xy, px); VPKFMA(py, P45, Rr[pc][1].xy, py); VPKFMA(px, P67, Rkk[c][1].zw, px); VPKFMA(py, P67, Rr[pc][1].zw, py);
;                         VADD(x, px.x, px.y); VADD(yp, py.x, py.y);
;                     } else {
;                         VPKMUL(px, P01, Rkk[c][0].xy); VPKFMA(px, P23, Rkk[c][0].zw, px); VPKFMA(px, P45, Rkk[c][1].xy, px); VPKFMA(px, P67, Rkk[c][1].zw, px);
;                         VADD(x, px.x, px.y);
;                     }
;                     asm volatile("" ::: "memory");
;                     if (s + 1 < 32) LOADREC((s + 1) & 1, s + 1);
;                     asm volatile("" ::: "memory");
;                     VPKMULBL(t01, vv2, Rkm[c][0].xy); VPKMULBL(t23, vv2, Rkm[c][0].zw);
;                     VDPP1(x); if (s >= 1) VDPP1(yp);
;                     VPKMULBL(t45, vv2, Rkm[c][1].xy); VPKMULBL(t67, vv2, Rkm[c][1].zw);
;                     VDPP2(x); if (s >= 1) VDPP2(yp);
;                     VPKFMA(P01, P01, Rw[c][0].xy, t01); VPKFMA(P23, P23, Rw[c][0].zw, t23);
;                     VDPP3(x); if (s >= 1) VDPP3(yp);
;                     VPKFMA(P45, P45, Rw[c][1].xy, t45); VPKFMA(P67, P67, Rw[c][1].zw, t67);
;                     if (s >= 1) { if (s - 1 < 8) YSHIFT(yk0); else if (s - 1 < 16) YSHIFT(yk1); else if (s - 1 < 24) YSHIFT(yk2); else YSHIFT(yk3); }
;                     x = x * si;
;                     f32x2 x2; x2.x = x; asm volatile("" : "+v"(x2));
;                     VPKNFMABL(P01, x2, Rka[c][0].xy, P01); VPKNFMABL(P23, x2, Rka[c][0].zw, P23); VPKNFMABL(P45, x2, Rka[c][1].xy, P45); VPKNFMABL(P67, x2, Rka[c][1].zw, P67);
;                 }
	ds_read_b128 v[80:83], v35 offset:6800
	ds_read_b128 v[84:87], v35 offset:6816
	ds_read_b128 v[104:107], v35 offset:32912
	ds_read_b128 v[108:111], v35 offset:32928
	ds_read_b32 v148, v36 offset:3200
	ds_read_b128 v[88:91], v35 offset:15504
	ds_read_b128 v[92:95], v35 offset:15520
	ds_read_b128 v[96:99], v35 offset:24208
	ds_read_b128 v[100:103], v35 offset:24224
	ds_read_b128 v[122:125], v35 offset:41616
	ds_read_b128 v[126:129], v35 offset:41632
	v_pk_mul_f32 v[8:9], v[4:5], v[48:49]
	v_pk_mul_f32 v[10:11], v[4:5], v[138:139]
	v_pk_fma_f32 v[8:9], v[6:7], v[50:51], v[8:9]
	v_pk_fma_f32 v[10:11], v[6:7], v[140:141], v[10:11]
	v_pk_fma_f32 v[8:9], v[0:1], v[52:53], v[8:9]
	v_pk_fma_f32 v[10:11], v[0:1], v[142:143], v[10:11]
	v_pk_fma_f32 v[8:9], v[2:3], v[54:55], v[8:9]
	v_pk_fma_f32 v[10:11], v[2:3], v[144:145], v[10:11]
	v_add_f32_e32 v12, v8, v9
	v_add_f32_e32 v14, v10, v11
	v_readlane_b32 s8, v34, 24
	v_pk_mul_f32 v[16:17], v[146:147], v[72:73] op_sel_hi:[0,1]
	v_pk_mul_f32 v[18:19], v[146:147], v[74:75] op_sel_hi:[0,1]
	v_add_f32_dpp v12, v12, v12 quad_perm:[1,0,3,2] row_mask:0xf bank_mask:0xf bound_ctrl:1
	v_add_f32_dpp v14, v14, v14 quad_perm:[1,0,3,2] row_mask:0xf bank_mask:0xf bound_ctrl:1
	v_pk_mul_f32 v[20:21], v[146:147], v[76:77] op_sel_hi:[0,1]
	v_pk_mul_f32 v[22:23], v[146:147], v[78:79] op_sel_hi:[0,1]
	v_add_f32_dpp v12, v12, v12 quad_perm:[2,3,0,1] row_mask:0xf bank_mask:0xf bound_ctrl:1
	v_add_f32_dpp v14, v14, v14 quad_perm:[2,3,0,1] row_mask:0xf bank_mask:0xf bound_ctrl:1
	v_pk_fma_f32 v[4:5], v[4:5], v[56:57], v[16:17]
	v_pk_fma_f32 v[6:7], v[6:7], v[58:59], v[18:19]
	v_add_f32_dpp v12, v12, v12 row_half_mirror row_mask:0xf bank_mask:0xf bound_ctrl:1
	v_add_f32_dpp v153, v14, v14 row_half_mirror row_mask:0xf bank_mask:0xa bound_ctrl:1
	v_pk_fma_f32 v[0:1], v[0:1], v[60:61], v[20:21]
	v_pk_fma_f32 v[2:3], v[2:3], v[62:63], v[22:23]
	v_mul_f32_e32 v12, s8, v12
	v_pk_fma_f32 v[4:5], v[12:13], v[64:65], v[4:5] op_sel_hi:[0,1,1] neg_lo:[1,0,0] neg_hi:[1,0,0]
	v_pk_fma_f32 v[6:7], v[12:13], v[66:67], v[6:7] op_sel_hi:[0,1,1] neg_lo:[1,0,0] neg_hi:[1,0,0]
	v_pk_fma_f32 v[0:1], v[12:13], v[68:69], v[0:1] op_sel_hi:[0,1,1] neg_lo:[1,0,0] neg_hi:[1,0,0]
	v_pk_fma_f32 v[2:3], v[12:13], v[70:71], v[2:3] op_sel_hi:[0,1,1] neg_lo:[1,0,0] neg_hi:[1,0,0]
	s_waitcnt lgkmcnt(0)
	ds_read_b128 v[48:51], v35 offset:7072
	ds_read_b128 v[52:55], v35 offset:7088
	ds_read_b128 v[72:75], v35 offset:33184
	ds_read_b128 v[76:79], v35 offset:33200
	ds_read_b32 v146, v36 offset:3328
	ds_read_b128 v[56:59], v35 offset:15776
	ds_read_b128 v[60:63], v35 offset:15792
	ds_read_b128 v[64:67], v35 offset:24480
	ds_read_b128 v[68:71], v35 offset:24496
	ds_read_b128 v[138:141], v35 offset:41888
	ds_read_b128 v[142:145], v35 offset:41904
	v_pk_mul_f32 v[8:9], v[4:5], v[80:81]
	v_pk_mul_f32 v[10:11], v[4:5], v[114:115]
	v_pk_fma_f32 v[8:9], v[6:7], v[82:83], v[8:9]
	v_pk_fma_f32 v[10:11], v[6:7], v[116:117], v[10:11]
	v_pk_fma_f32 v[8:9], v[0:1], v[84:85], v[8:9]
	v_pk_fma_f32 v[10:11], v[0:1], v[118:119], v[10:11]
	v_pk_fma_f32 v[8:9], v[2:3], v[86:87], v[8:9]
	v_pk_fma_f32 v[10:11], v[2:3], v[120:121], v[10:11]
	v_add_f32_e32 v12, v8, v9
	v_add_f32_e32 v14, v10, v11
	v_readlane_b32 s8, v34, 25
	v_pk_mul_f32 v[16:17], v[148:149], v[104:105] op_sel_hi:[0,1]
	v_pk_mul_f32 v[18:19], v[148:149], v[106:107] op_sel_hi:[0,1]
	v_add_f32_dpp v12, v12, v12 quad_perm:[1,0,3,2] row_mask:0xf bank_mask:0xf bound_ctrl:1
	v_add_f32_dpp v14, v14, v14 quad_perm:[1,0,3,2] row_mask:0xf bank_mask:0xf bound_ctrl:1
	v_pk_mul_f32 v[20:21], v[148:149], v[108:109] op_sel_hi:[0,1]
	v_pk_mul_f32 v[22:23], v[148:149], v[110:111] op_sel_hi:[0,1]
	v_add_f32_dpp v12, v12, v12 quad_perm:[2,3,0,1] row_mask:0xf bank_mask:0xf bound_ctrl:1
	v_add_f32_dpp v14, v14, v14 quad_perm:[2,3,0,1] row_mask:0xf bank_mask:0xf bound_ctrl:1
	v_pk_fma_f32 v[4:5], v[4:5], v[88:89], v[16:17]
	v_pk_fma_f32 v[6:7], v[6:7], v[90:91], v[18:19]
	v_add_f32_dpp v12, v12, v12 row_half_mirror row_mask:0xf bank_mask:0xf bound_ctrl:1
	v_add_f32_dpp v154, v14, v14 row_half_mirror row_mask:0xf bank_mask:0x5 bound_ctrl:1
	v_pk_fma_f32 v[0:1], v[0:1], v[92:93], v[20:21]
	v_pk_fma_f32 v[2:3], v[2:3], v[94:95], v[22:23]
	v_mul_f32_e32 v12, s8, v12
	v_pk_fma_f32 v[4:5], v[12:13], v[96:97], v[4:5] op_sel_hi:[0,1,1] neg_lo:[1,0,0] neg_hi:[1,0,0]
	v_pk_fma_f32 v[6:7], v[12:13], v[98:99], v[6:7] op_sel_hi:[0,1,1] neg_lo:[1,0,0] neg_hi:[1,0,0]
	v_pk_fma_f32 v[0:1], v[12:13], v[100:101], v[0:1] op_sel_hi:[0,1,1] neg_lo:[1,0,0] neg_hi:[1,0,0]
	v_pk_fma_f32 v[2:3], v[12:13], v[102:103], v[2:3] op_sel_hi:[0,1,1] neg_lo:[1,0,0] neg_hi:[1,0,0]
	s_waitcnt lgkmcnt(0)
; __device__ __forceinline__ void scan_half(const Params& p, LAS unsigned char* lds, int pi, int rh, int pass) {
;     ...
;                 for (int s = 0; s < 32; ++s) {
;                     const int c = s & 1, pc = c ^ 1;
;                     const float si = __int_as_float(__builtin_amdgcn_readlane(__float_as_int(inv2), s));
;                     f32x2 px, py, t01, t23, t45, t67; float x;
;                     f32x2 vv2; vv2.x = Rv[c]; asm volatile("" : "+v"(vv2));
;                     if (s >= 1) {
;                         VPKMUL(px, P01, Rkk[c][0].xy); VPKMUL(py, P01, Rr[pc][0].xy); VPKFMA(px, P23, Rkk[c][0].zw, px); VPKFMA(py, P23, Rr[pc][0].zw, py);
;                         VPKFMA(px, P45, Rkk[c][1].xy, px); VPKFMA(py, P45, Rr[pc][1].xy, py); VPKFMA(px, P67, Rkk[c][1].zw, px); VPKFMA(py, P67, Rr[pc][1].zw, py);
;                         VADD(x, px.x, px.y); VADD(yp, py.x, py.y);
;                     } else {
;                         VPKMUL(px, P01, Rkk[c][0].xy); VPKFMA(px, P23, Rkk[c][0].zw, px); VPKFMA(px, P45, Rkk[c][1].xy, px); VPKFMA(px, P67, Rkk[c][1].zw, px);
;                         VADD(x, px.x, px.y);
;                     }
;                     asm volatile("" ::: "memory");
;                     if (s + 1 < 32) LOADREC((s + 1) & 1, s + 1);
;                     asm volatile("" ::: "memory");
;                     VPKMULBL(t01, vv2, Rkm[c][0].xy); VPKMULBL(t23, vv2, Rkm[c][0].zw);
;                     VDPP1(x); if (s >= 1) VDPP1(yp);
;                     VPKMULBL(t45, vv2, Rkm[c][1].xy); VPKMULBL(t67, vv2, Rkm[c][1].zw);
;                     VDPP2(x); if (s >= 1) VDPP2(yp);
;                     VPKFMA(P01, P01, Rw[c][0].xy, t01); VPKFMA(P23, P23, Rw[c][0].zw, t23);
;                     VDPP3(x); if (s >= 1) VDPP3(yp);
;                     VPKFMA(P45, P45, Rw[c][1].xy, t45); VPKFMA(P67, P67, Rw[c][1].zw, t67);
;                     if (s >= 1) { if (s - 1 < 8) YSHIFT(yk0); else if (s - 1 < 16) YSHIFT(yk1); else if (s - 1 < 24) YSHIFT(yk2); else YSHIFT(yk3); }
;                     x = x * si;
;                     f32x2 x2; x2.x = x; asm volatile("" : "+v"(x2));
;                     VPKNFMABL(P01, x2, Rka[c][0].xy, P01); VPKNFMABL(P23, x2, Rka[c][0].zw, P23); VPKNFMABL(P45, x2, Rka[c][1].xy, P45); VPKNFMABL(P67, x2, Rka[c][1].zw, P67);
;                 }
	ds_read_b128 v[80:83], v35 offset:7344
	ds_read_b128 v[84:87], v35 offset:7360
	ds_read_b128 v[104:107], v35 offset:33456
	ds_read_b128 v[108:111], v35 offset:33472
	ds_read_b32 v148, v36 offset:3456
	ds_read_b128 v[88:91], v35 offset:16048
	ds_read_b128 v[92:95], v35 offset:16064
	ds_read_b128 v[96:99], v35 offset:24752
	ds_read_b128 v[100:103], v35 offset:24768
	ds_read_b128 v[114:117], v35 offset:42160
	ds_read_b128 v[118:121], v35 offset:42176
	v_pk_mul_f32 v[8:9], v[4:5], v[48:49]
	v_pk_mul_f32 v[10:11], v[4:5], v[122:123]
	v_pk_fma_f32 v[8:9], v[6:7], v[50:51], v[8:9]
	v_pk_fma_f32 v[10:11], v[6:7], v[124:125], v[10:11]
	v_pk_fma_f32 v[8:9], v[0:1], v[52:53], v[8:9]
	v_pk_fma_f32 v[10:11], v[0:1], v[126:127], v[10:11]
	v_pk_fma_f32 v[8:9], v[2:3], v[54:55], v[8:9]
	v_pk_fma_f32 v[10:11], v[2:3], v[128:129], v[10:11]
	v_add_f32_e32 v12, v8, v9
	v_add_f32_e32 v14, v10, v11
	v_readlane_b32 s8, v34, 26
	v_pk_mul_f32 v[16:17], v[146:147], v[72:73] op_sel_hi:[0,1]
	v_pk_mul_f32 v[18:19], v[146:147], v[74:75] op_sel_hi:[0,1]
	v_add_f32_dpp v12, v12, v12 quad_perm:[1,0,3,2] row_mask:0xf bank_mask:0xf bound_ctrl:1
	v_add_f32_dpp v14, v14, v14 quad_perm:[1,0,3,2] row_mask:0xf bank_mask:0xf bound_ctrl:1
	v_pk_mul_f32 v[20:21], v[146:147], v[76:77] op_sel_hi:[0,1]
	v_pk_mul_f32 v[22:23], v[146:147], v[78:79] op_sel_hi:[0,1]
	v_add_f32_dpp v12, v12, v12 quad_perm:[2,3,0,1] row_mask:0xf bank_mask:0xf bound_ctrl:1
	v_add_f32_dpp v14, v14, v14 quad_perm:[2,3,0,1] row_mask:0xf bank_mask:0xf bound_ctrl:1
	v_pk_fma_f32 v[4:5], v[4:5], v[56:57], v[16:17]
	v_pk_fma_f32 v[6:7], v[6:7], v[58:59], v[18:19]
	v_add_f32_dpp v12, v12, v12 row_half_mirror row_mask:0xf bank_mask:0xf bound_ctrl:1
	v_add_f32_dpp v154, v14, v14 row_half_mirror row_mask:0xf bank_mask:0xa bound_ctrl:1
	v_pk_fma_f32 v[0:1], v[0:1], v[60:61], v[20:21]
	v_pk_fma_f32 v[2:3], v[2:3], v[62:63], v[22:23]
	v_mul_f32_e32 v12, s8, v12
	v_pk_fma_f32 v[4:5], v[12:13], v[64:65], v[4:5] op_sel_hi:[0,1,1] neg_lo:[1,0,0] neg_hi:[1,0,0]
	v_pk_fma_f32 v[6:7], v[12:13], v[66:67], v[6:7] op_sel_hi:[0,1,1] neg_lo:[1,0,0] neg_hi:[1,0,0]
	v_pk_fma_f32 v[0:1], v[12:13], v[68:69], v[0:1] op_sel_hi:[0,1,1] neg_lo:[1,0,0] neg_hi:[1,0,0]
	v_pk_fma_f32 v[2:3], v[12:13], v[70:71], v[2:3] op_sel_hi:[0,1,1] neg_lo:[1,0,0] neg_hi:[1,0,0]
	s_waitcnt lgkmcnt(0)
	ds_read_b128 v[48:51], v35 offset:7616
	ds_read_b128 v[52:55], v35 offset:7632
	ds_read_b128 v[72:75], v35 offset:33728
	ds_read_b128 v[76:79], v35 offset:33744
	ds_read_b32 v146, v36 offset:3584
	ds_read_b128 v[56:59], v35 offset:16320
	ds_read_b128 v[60:63], v35 offset:16336
	ds_read_b128 v[64:67], v35 offset:25024
	ds_read_b128 v[68:71], v35 offset:25040
	ds_read_b128 v[122:125], v35 offset:42432
	ds_read_b128 v[126:129], v35 offset:42448
	v_pk_mul_f32 v[8:9], v[4:5], v[80:81]
	v_pk_mul_f32 v[10:11], v[4:5], v[138:139]
	v_pk_fma_f32 v[8:9], v[6:7], v[82:83], v[8:9]
	v_pk_fma_f32 v[10:11], v[6:7], v[140:141], v[10:11]
	v_pk_fma_f32 v[8:9], v[0:1], v[84:85], v[8:9]
	v_pk_fma_f32 v[10:11], v[0:1], v[142:143], v[10:11]
	v_pk_fma_f32 v[8:9], v[2:3], v[86:87], v[8:9]
	v_pk_fma_f32 v[10:11], v[2:3], v[144:145], v[10:11]
	v_add_f32_e32 v12, v8, v9
	v_add_f32_e32 v14, v10, v11
	v_readlane_b32 s8, v34, 27
	v_pk_mul_f32 v[16:17], v[148:149], v[104:105] op_sel_hi:[0,1]
	v_pk_mul_f32 v[18:19], v[148:149], v[106:107] op_sel_hi:[0,1]
	v_add_f32_dpp v12, v12, v12 quad_perm:[1,0,3,2] row_mask:0xf bank_mask:0xf bound_ctrl:1
	v_add_f32_dpp v14, v14, v14 quad_perm:[1,0,3,2] row_mask:0xf bank_mask:0xf bound_ctrl:1
	v_pk_mul_f32 v[20:21], v[148:149], v[108:109] op_sel_hi:[0,1]
	v_pk_mul_f32 v[22:23], v[148:149], v[110:111] op_sel_hi:[0,1]
	v_add_f32_dpp v12, v12, v12 quad_perm:[2,3,0,1] row_mask:0xf bank_mask:0xf bound_ctrl:1
	v_add_f32_dpp v14, v14, v14 quad_perm:[2,3,0,1] row_mask:0xf bank_mask:0xf bound_ctrl:1
	v_pk_fma_f32 v[4:5], v[4:5], v[88:89], v[16:17]
	v_pk_fma_f32 v[6:7], v[6:7], v[90:91], v[18:19]
	v_add_f32_dpp v12, v12, v12 row_half_mirror row_mask:0xf bank_mask:0xf bound_ctrl:1
	v_add_f32_dpp v155, v14, v14 row_half_mirror row_mask:0xf bank_mask:0x5 bound_ctrl:1
	v_pk_fma_f32 v[0:1], v[0:1], v[92:93], v[20:21]
	v_pk_fma_f32 v[2:3], v[2:3], v[94:95], v[22:23]
	v_mul_f32_e32 v12, s8, v12
	v_pk_fma_f32 v[4:5], v[12:13], v[96:97], v[4:5] op_sel_hi:[0,1,1] neg_lo:[1,0,0] neg_hi:[1,0,0]
	v_pk_fma_f32 v[6:7], v[12:13], v[98:99], v[6:7] op_sel_hi:[0,1,1] neg_lo:[1,0,0] neg_hi:[1,0,0]
	v_pk_fma_f32 v[0:1], v[12:13], v[100:101], v[0:1] op_sel_hi:[0,1,1] neg_lo:[1,0,0] neg_hi:[1,0,0]
	v_pk_fma_f32 v[2:3], v[12:13], v[102:103], v[2:3] op_sel_hi:[0,1,1] neg_lo:[1,0,0] neg_hi:[1,0,0]
	s_waitcnt lgkmcnt(0)
; __device__ __forceinline__ void scan_half(const Params& p, LAS unsigned char* lds, int pi, int rh, int pass) {
;     ...
;                 for (int s = 0; s < 32; ++s) {
;                     const int c = s & 1, pc = c ^ 1;
;                     const float si = __int_as_float(__builtin_amdgcn_readlane(__float_as_int(inv2), s));
;                     f32x2 px, py, t01, t23, t45, t67; float x;
;                     f32x2 vv2; vv2.x = Rv[c]; asm volatile("" : "+v"(vv2));
;                     if (s >= 1) {
;                         VPKMUL(px, P01, Rkk[c][0].xy); VPKMUL(py, P01, Rr[pc][0].xy); VPKFMA(px, P23, Rkk[c][0].zw, px); VPKFMA(py, P23, Rr[pc][0].zw, py);
;                         VPKFMA(px, P45, Rkk[c][1].xy, px); VPKFMA(py, P45, Rr[pc][1].xy, py); VPKFMA(px, P67, Rkk[c][1].zw, px); VPKFMA(py, P67, Rr[pc][1].zw, py);
;                         VADD(x, px.x, px.y); VADD(yp, py.x, py.y);
;                     } else {
;                         VPKMUL(px, P01, Rkk[c][0].xy); VPKFMA(px, P23, Rkk[c][0].zw, px); VPKFMA(px, P45, Rkk[c][1].xy, px); VPKFMA(px, P67, Rkk[c][1].zw, px);
;                         VADD(x, px.x, px.y);
;                     }
;                     asm volatile("" ::: "memory");
;                     if (s + 1 < 32) LOADREC((s + 1) & 1, s + 1);
;                     asm volatile("" ::: "memory");
;                     VPKMULBL(t01, vv2, Rkm[c][0].xy); VPKMULBL(t23, vv2, Rkm[c][0].zw);
;                     VDPP1(x); if (s >= 1) VDPP1(yp);
;                     VPKMULBL(t45, vv2, Rkm[c][1].xy); VPKMULBL(t67, vv2, Rkm[c][1].zw);
;                     VDPP2(x); if (s >= 1) VDPP2(yp);
;                     VPKFMA(P01, P01, Rw[c][0].xy, t01); VPKFMA(P23, P23, Rw[c][0].zw, t23);
;                     VDPP3(x); if (s >= 1) VDPP3(yp);
;                     VPKFMA(P45, P45, Rw[c][1].xy, t45); VPKFMA(P67, P67, Rw[c][1].zw, t67);
;                     if (s >= 1) { if (s - 1 < 8) YSHIFT(yk0); else if (s - 1 < 16) YSHIFT(yk1); else if (s - 1 < 24) YSHIFT(yk2); else YSHIFT(yk3); }
;                     x = x * si;
;                     f32x2 x2; x2.x = x; asm volatile("" : "+v"(x2));
;                     VPKNFMABL(P01, x2, Rka[c][0].xy, P01); VPKNFMABL(P23, x2, Rka[c][0].zw, P23); VPKNFMABL(P45, x2, Rka[c][1].xy, P45); VPKNFMABL(P67, x2, Rka[c][1].zw, P67);
;                 }
	ds_read_b128 v[80:83], v35 offset:7888
	ds_read_b128 v[84:87], v35 offset:7904
	ds_read_b128 v[104:107], v35 offset:34000
	ds_read_b128 v[108:111], v35 offset:34016
	ds_read_b32 v148, v36 offset:3712
	ds_read_b128 v[88:91], v35 offset:16592
	ds_read_b128 v[92:95], v35 offset:16608
	ds_read_b128 v[96:99], v35 offset:25296
	ds_read_b128 v[100:103], v35 offset:25312
	ds_read_b128 v[138:141], v35 offset:42704
	ds_read_b128 v[142:145], v35 offset:42720
	v_pk_mul_f32 v[8:9], v[4:5], v[48:49]
	v_pk_mul_f32 v[10:11], v[4:5], v[114:115]
	v_pk_fma_f32 v[8:9], v[6:7], v[50:51], v[8:9]
	v_pk_fma_f32 v[10:11], v[6:7], v[116:117], v[10:11]
	v_pk_fma_f32 v[8:9], v[0:1], v[52:53], v[8:9]
	v_pk_fma_f32 v[10:11], v[0:1], v[118:119], v[10:11]
	v_pk_fma_f32 v[8:9], v[2:3], v[54:55], v[8:9]
	v_pk_fma_f32 v[10:11], v[2:3], v[120:121], v[10:11]
	v_add_f32_e32 v12, v8, v9
	v_add_f32_e32 v14, v10, v11
	v_readlane_b32 s8, v34, 28
	v_pk_mul_f32 v[16:17], v[146:147], v[72:73] op_sel_hi:[0,1]
	v_pk_mul_f32 v[18:19], v[146:147], v[74:75] op_sel_hi:[0,1]
	v_add_f32_dpp v12, v12, v12 quad_perm:[1,0,3,2] row_mask:0xf bank_mask:0xf bound_ctrl:1
	v_add_f32_dpp v14, v14, v14 quad_perm:[1,0,3,2] row_mask:0xf bank_mask:0xf bound_ctrl:1
	v_pk_mul_f32 v[20:21], v[146:147], v[76:77] op_sel_hi:[0,1]
	v_pk_mul_f32 v[22:23], v[146:147], v[78:79] op_sel_hi:[0,1]
	v_add_f32_dpp v12, v12, v12 quad_perm:[2,3,0,1] row_mask:0xf bank_mask:0xf bound_ctrl:1
	v_add_f32_dpp v14, v14, v14 quad_perm:[2,3,0,1] row_mask:0xf bank_mask:0xf bound_ctrl:1
	v_pk_fma_f32 v[4:5], v[4:5], v[56:57], v[16:17]
	v_pk_fma_f32 v[6:7], v[6:7], v[58:59], v[18:19]
	v_add_f32_dpp v12, v12, v12 row_half_mirror row_mask:0xf bank_mask:0xf bound_ctrl:1
	v_add_f32_dpp v155, v14, v14 row_half_mirror row_mask:0xf bank_mask:0xa bound_ctrl:1
	v_pk_fma_f32 v[0:1], v[0:1], v[60:61], v[20:21]
	v_pk_fma_f32 v[2:3], v[2:3], v[62:63], v[22:23]
	v_mul_f32_e32 v12, s8, v12
	v_pk_fma_f32 v[4:5], v[12:13], v[64:65], v[4:5] op_sel_hi:[0,1,1] neg_lo:[1,0,0] neg_hi:[1,0,0]
	v_pk_fma_f32 v[6:7], v[12:13], v[66:67], v[6:7] op_sel_hi:[0,1,1] neg_lo:[1,0,0] neg_hi:[1,0,0]
	v_pk_fma_f32 v[0:1], v[12:13], v[68:69], v[0:1] op_sel_hi:[0,1,1] neg_lo:[1,0,0] neg_hi:[1,0,0]
	v_pk_fma_f32 v[2:3], v[12:13], v[70:71], v[2:3] op_sel_hi:[0,1,1] neg_lo:[1,0,0] neg_hi:[1,0,0]
	s_waitcnt lgkmcnt(0)
	ds_read_b128 v[48:51], v35 offset:8160
	ds_read_b128 v[52:55], v35 offset:8176
	ds_read_b128 v[72:75], v35 offset:34272
	ds_read_b128 v[76:79], v35 offset:34288
	ds_read_b32 v146, v36 offset:3840
	ds_read_b128 v[56:59], v35 offset:16864
	ds_read_b128 v[60:63], v35 offset:16880
	ds_read_b128 v[64:67], v35 offset:25568
	ds_read_b128 v[68:71], v35 offset:25584
	ds_read_b128 v[114:117], v35 offset:42976
	ds_read_b128 v[118:121], v35 offset:42992
	v_pk_mul_f32 v[8:9], v[4:5], v[80:81]
	v_pk_mul_f32 v[10:11], v[4:5], v[122:123]
	v_pk_fma_f32 v[8:9], v[6:7], v[82:83], v[8:9]
	v_pk_fma_f32 v[10:11], v[6:7], v[124:125], v[10:11]
	v_pk_fma_f32 v[8:9], v[0:1], v[84:85], v[8:9]
	v_pk_fma_f32 v[10:11], v[0:1], v[126:127], v[10:11]
	v_pk_fma_f32 v[8:9], v[2:3], v[86:87], v[8:9]
	v_pk_fma_f32 v[10:11], v[2:3], v[128:129], v[10:11]
	v_add_f32_e32 v12, v8, v9
	v_add_f32_e32 v14, v10, v11
	v_readlane_b32 s8, v34, 29
	v_pk_mul_f32 v[16:17], v[148:149], v[104:105] op_sel_hi:[0,1]
	v_pk_mul_f32 v[18:19], v[148:149], v[106:107] op_sel_hi:[0,1]
	v_add_f32_dpp v12, v12, v12 quad_perm:[1,0,3,2] row_mask:0xf bank_mask:0xf bound_ctrl:1
	v_add_f32_dpp v14, v14, v14 quad_perm:[1,0,3,2] row_mask:0xf bank_mask:0xf bound_ctrl:1
	v_pk_mul_f32 v[20:21], v[148:149], v[108:109] op_sel_hi:[0,1]
	v_pk_mul_f32 v[22:23], v[148:149], v[110:111] op_sel_hi:[0,1]
	v_add_f32_dpp v12, v12, v12 quad_perm:[2,3,0,1] row_mask:0xf bank_mask:0xf bound_ctrl:1
	v_add_f32_dpp v14, v14, v14 quad_perm:[2,3,0,1] row_mask:0xf bank_mask:0xf bound_ctrl:1
	v_pk_fma_f32 v[4:5], v[4:5], v[88:89], v[16:17]
	v_pk_fma_f32 v[6:7], v[6:7], v[90:91], v[18:19]
	v_add_f32_dpp v12, v12, v12 row_half_mirror row_mask:0xf bank_mask:0xf bound_ctrl:1
	v_add_f32_dpp v156, v14, v14 row_half_mirror row_mask:0xf bank_mask:0x5 bound_ctrl:1
	v_pk_fma_f32 v[0:1], v[0:1], v[92:93], v[20:21]
	v_pk_fma_f32 v[2:3], v[2:3], v[94:95], v[22:23]
	v_mul_f32_e32 v12, s8, v12
	v_pk_fma_f32 v[4:5], v[12:13], v[96:97], v[4:5] op_sel_hi:[0,1,1] neg_lo:[1,0,0] neg_hi:[1,0,0]
	v_pk_fma_f32 v[6:7], v[12:13], v[98:99], v[6:7] op_sel_hi:[0,1,1] neg_lo:[1,0,0] neg_hi:[1,0,0]
	v_pk_fma_f32 v[0:1], v[12:13], v[100:101], v[0:1] op_sel_hi:[0,1,1] neg_lo:[1,0,0] neg_hi:[1,0,0]
	v_pk_fma_f32 v[2:3], v[12:13], v[102:103], v[2:3] op_sel_hi:[0,1,1] neg_lo:[1,0,0] neg_hi:[1,0,0]
	s_waitcnt lgkmcnt(0)
; __device__ __forceinline__ void scan_half(const Params& p, LAS unsigned char* lds, int pi, int rh, int pass) {
;     ...
;                 for (int s = 0; s < 32; ++s) {
;                     const int c = s & 1, pc = c ^ 1;
;                     const float si = __int_as_float(__builtin_amdgcn_readlane(__float_as_int(inv2), s));
;                     f32x2 px, py, t01, t23, t45, t67; float x;
;                     f32x2 vv2; vv2.x = Rv[c]; asm volatile("" : "+v"(vv2));
;                     if (s >= 1) {
;                         VPKMUL(px, P01, Rkk[c][0].xy); VPKMUL(py, P01, Rr[pc][0].xy); VPKFMA(px, P23, Rkk[c][0].zw, px); VPKFMA(py, P23, Rr[pc][0].zw, py);
;                         VPKFMA(px, P45, Rkk[c][1].xy, px); VPKFMA(py, P45, Rr[pc][1].xy, py); VPKFMA(px, P67, Rkk[c][1].zw, px); VPKFMA(py, P67, Rr[pc][1].zw, py);
;                         VADD(x, px.x, px.y); VADD(yp, py.x, py.y);
;                     } else {
;                         VPKMUL(px, P01, Rkk[c][0].xy); VPKFMA(px, P23, Rkk[c][0].zw, px); VPKFMA(px, P45, Rkk[c][1].xy, px); VPKFMA(px, P67, Rkk[c][1].zw, px);
;                         VADD(x, px.x, px.y);
;                     }
;                     asm volatile("" ::: "memory");
;                     if (s + 1 < 32) LOADREC((s + 1) & 1, s + 1);
;                     asm volatile("" ::: "memory");
;                     VPKMULBL(t01, vv2, Rkm[c][0].xy); VPKMULBL(t23, vv2, Rkm[c][0].zw);
;                     VDPP1(x); if (s >= 1) VDPP1(yp);
;                     VPKMULBL(t45, vv2, Rkm[c][1].xy); VPKMULBL(t67, vv2, Rkm[c][1].zw);
;                     VDPP2(x); if (s >= 1) VDPP2(yp);
;                     VPKFMA(P01, P01, Rw[c][0].xy, t01); VPKFMA(P23, P23, Rw[c][0].zw, t23);
;                     VDPP3(x); if (s >= 1) VDPP3(yp);
;                     VPKFMA(P45, P45, Rw[c][1].xy, t45); VPKFMA(P67, P67, Rw[c][1].zw, t67);
;                     if (s >= 1) { if (s - 1 < 8) YSHIFT(yk0); else if (s - 1 < 16) YSHIFT(yk1); else if (s - 1 < 24) YSHIFT(yk2); else YSHIFT(yk3); }
;                     x = x * si;
;                     f32x2 x2; x2.x = x; asm volatile("" : "+v"(x2));
;                     VPKNFMABL(P01, x2, Rka[c][0].xy, P01); VPKNFMABL(P23, x2, Rka[c][0].zw, P23); VPKNFMABL(P45, x2, Rka[c][1].xy, P45); VPKNFMABL(P67, x2, Rka[c][1].zw, P67);
;                 }
	ds_read_b128 v[80:83], v35 offset:8432
	ds_read_b128 v[84:87], v35 offset:8448
	ds_read_b128 v[104:107], v35 offset:34544
	ds_read_b128 v[108:111], v35 offset:34560
	ds_read_b32 v148, v36 offset:3968
	ds_read_b128 v[88:91], v35 offset:17136
	ds_read_b128 v[92:95], v35 offset:17152
	ds_read_b128 v[96:99], v35 offset:25840
	ds_read_b128 v[100:103], v35 offset:25856
	ds_read_b128 v[122:125], v35 offset:43248
	ds_read_b128 v[126:129], v35 offset:43264
	v_pk_mul_f32 v[8:9], v[4:5], v[48:49]
	v_pk_mul_f32 v[10:11], v[4:5], v[138:139]
	v_pk_fma_f32 v[8:9], v[6:7], v[50:51], v[8:9]
	v_pk_fma_f32 v[10:11], v[6:7], v[140:141], v[10:11]
	v_pk_fma_f32 v[8:9], v[0:1], v[52:53], v[8:9]
	v_pk_fma_f32 v[10:11], v[0:1], v[142:143], v[10:11]
	v_pk_fma_f32 v[8:9], v[2:3], v[54:55], v[8:9]
	v_pk_fma_f32 v[10:11], v[2:3], v[144:145], v[10:11]
	v_add_f32_e32 v12, v8, v9
	v_add_f32_e32 v14, v10, v11
	v_readlane_b32 s8, v34, 30
	v_pk_mul_f32 v[16:17], v[146:147], v[72:73] op_sel_hi:[0,1]
	v_pk_mul_f32 v[18:19], v[146:147], v[74:75] op_sel_hi:[0,1]
	v_add_f32_dpp v12, v12, v12 quad_perm:[1,0,3,2] row_mask:0xf bank_mask:0xf bound_ctrl:1
	v_add_f32_dpp v14, v14, v14 quad_perm:[1,0,3,2] row_mask:0xf bank_mask:0xf bound_ctrl:1
	v_pk_mul_f32 v[20:21], v[146:147], v[76:77] op_sel_hi:[0,1]
	v_pk_mul_f32 v[22:23], v[146:147], v[78:79] op_sel_hi:[0,1]
	v_add_f32_dpp v12, v12, v12 quad_perm:[2,3,0,1] row_mask:0xf bank_mask:0xf bound_ctrl:1
	v_add_f32_dpp v14, v14, v14 quad_perm:[2,3,0,1] row_mask:0xf bank_mask:0xf bound_ctrl:1
	v_pk_fma_f32 v[4:5], v[4:5], v[56:57], v[16:17]
	v_pk_fma_f32 v[6:7], v[6:7], v[58:59], v[18:19]
	v_add_f32_dpp v12, v12, v12 row_half_mirror row_mask:0xf bank_mask:0xf bound_ctrl:1
	v_add_f32_dpp v156, v14, v14 row_half_mirror row_mask:0xf bank_mask:0xa bound_ctrl:1
	v_pk_fma_f32 v[0:1], v[0:1], v[60:61], v[20:21]
	v_pk_fma_f32 v[2:3], v[2:3], v[62:63], v[22:23]
	v_mul_f32_e32 v12, s8, v12
	v_pk_fma_f32 v[4:5], v[12:13], v[64:65], v[4:5] op_sel_hi:[0,1,1] neg_lo:[1,0,0] neg_hi:[1,0,0]
	v_pk_fma_f32 v[6:7], v[12:13], v[66:67], v[6:7] op_sel_hi:[0,1,1] neg_lo:[1,0,0] neg_hi:[1,0,0]
	v_pk_fma_f32 v[0:1], v[12:13], v[68:69], v[0:1] op_sel_hi:[0,1,1] neg_lo:[1,0,0] neg_hi:[1,0,0]
	v_pk_fma_f32 v[2:3], v[12:13], v[70:71], v[2:3] op_sel_hi:[0,1,1] neg_lo:[1,0,0] neg_hi:[1,0,0]
	s_waitcnt lgkmcnt(0)
	v_pk_mul_f32 v[8:9], v[4:5], v[80:81]
	v_pk_mul_f32 v[10:11], v[4:5], v[114:115]
	v_pk_fma_f32 v[8:9], v[6:7], v[82:83], v[8:9]
	v_pk_fma_f32 v[10:11], v[6:7], v[116:117], v[10:11]
	v_pk_fma_f32 v[8:9], v[0:1], v[84:85], v[8:9]
	v_pk_fma_f32 v[10:11], v[0:1], v[118:119], v[10:11]
	v_pk_fma_f32 v[8:9], v[2:3], v[86:87], v[8:9]
	v_pk_fma_f32 v[10:11], v[2:3], v[120:121], v[10:11]
	v_add_f32_e32 v12, v8, v9
	v_add_f32_e32 v14, v10, v11
	v_readlane_b32 s8, v34, 31
	v_pk_mul_f32 v[16:17], v[148:149], v[104:105] op_sel_hi:[0,1]
	v_pk_mul_f32 v[18:19], v[148:149], v[106:107] op_sel_hi:[0,1]
	v_add_f32_dpp v12, v12, v12 quad_perm:[1,0,3,2] row_mask:0xf bank_mask:0xf bound_ctrl:1
	v_add_f32_dpp v14, v14, v14 quad_perm:[1,0,3,2] row_mask:0xf bank_mask:0xf bound_ctrl:1
	v_pk_mul_f32 v[20:21], v[148:149], v[108:109] op_sel_hi:[0,1]
	v_pk_mul_f32 v[22:23], v[148:149], v[110:111] op_sel_hi:[0,1]
	v_add_f32_dpp v12, v12, v12 quad_perm:[2,3,0,1] row_mask:0xf bank_mask:0xf bound_ctrl:1
	v_add_f32_dpp v14, v14, v14 quad_perm:[2,3,0,1] row_mask:0xf bank_mask:0xf bound_ctrl:1
	v_pk_fma_f32 v[4:5], v[4:5], v[88:89], v[16:17]
	v_pk_fma_f32 v[6:7], v[6:7], v[90:91], v[18:19]
	v_add_f32_dpp v12, v12, v12 row_half_mirror row_mask:0xf bank_mask:0xf bound_ctrl:1
	v_add_f32_dpp v157, v14, v14 row_half_mirror row_mask:0xf bank_mask:0x5 bound_ctrl:1
	v_pk_fma_f32 v[0:1], v[0:1], v[92:93], v[20:21]
	v_pk_fma_f32 v[2:3], v[2:3], v[94:95], v[22:23]
	v_mul_f32_e32 v12, s8, v12
	v_pk_fma_f32 v[4:5], v[12:13], v[96:97], v[4:5] op_sel_hi:[0,1,1] neg_lo:[1,0,0] neg_hi:[1,0,0]
	v_pk_fma_f32 v[6:7], v[12:13], v[98:99], v[6:7] op_sel_hi:[0,1,1] neg_lo:[1,0,0] neg_hi:[1,0,0]
	v_pk_fma_f32 v[0:1], v[12:13], v[100:101], v[0:1] op_sel_hi:[0,1,1] neg_lo:[1,0,0] neg_hi:[1,0,0]
	v_pk_fma_f32 v[2:3], v[12:13], v[102:103], v[2:3] op_sel_hi:[0,1,1] neg_lo:[1,0,0] neg_hi:[1,0,0]
	v_pk_mul_f32 v[10:11], v[4:5], v[122:123]
	v_pk_fma_f32 v[10:11], v[6:7], v[124:125], v[10:11]
	v_pk_fma_f32 v[10:11], v[0:1], v[126:127], v[10:11]
	v_pk_fma_f32 v[10:11], v[2:3], v[128:129], v[10:11]
	v_add_f32_e32 v14, v10, v11
	s_nop 1
	v_add_f32_dpp v14, v14, v14 quad_perm:[1,0,3,2] row_mask:0xf bank_mask:0xf bound_ctrl:1
	s_nop 1
	v_add_f32_dpp v14, v14, v14 quad_perm:[2,3,0,1] row_mask:0xf bank_mask:0xf bound_ctrl:1
	s_nop 1
	v_add_f32_dpp v157, v14, v14 row_half_mirror row_mask:0xf bank_mask:0xa bound_ctrl:1
	ds_write_b32 v37, v40 offset:0
	ds_write_b32 v37, v41 offset:256
	ds_write_b32 v37, v42 offset:512
	ds_write_b32 v37, v43 offset:768
	ds_write_b32 v37, v44 offset:1024
	ds_write_b32 v37, v45 offset:1280
	ds_write_b32 v37, v46 offset:1536
	ds_write_b32 v37, v47 offset:1792
	ds_write_b32 v37, v150 offset:2048
	ds_write_b32 v37, v151 offset:2304
	ds_write_b32 v37, v152 offset:2560
	ds_write_b32 v37, v153 offset:2816
	ds_write_b32 v37, v154 offset:3072
	ds_write_b32 v37, v155 offset:3328
	ds_write_b32 v37, v156 offset:3584
	ds_write_b32 v37, v157 offset:3840
.Lscan_bar:
	s_waitcnt lgkmcnt(0)
	s_barrier
	s_add_i32 s9, s9, 1
	s_cmpk_eq_i32 s9, 0x42
	s_cbranch_scc0 .Lscan_it
